# RES and PLE2 epilogues: row-sum atomics deferred to the end of the epilogue
# baseline (speedup 1.0000x reference)
.LBB0_360:
	v_lshl_add_u32 v158, s40, 8, v153
	s_mov_b64 s[26:27], -1
	s_mov_b64 s[78:79], 0
	s_cmp_lt_i32 s96, 5
	s_mov_b64 s[40:41], 0
	s_cbranch_scc1 .LBB0_388
	s_cmp_gt_i32 s96, 5
	s_cbranch_scc0 .LBB0_385
	s_cmp_gt_i32 s96, 6
	s_mov_b64 s[40:41], -1
	s_cbranch_scc0 .LBB0_384
	s_cmp_lg_u32 s96, 7
	s_cbranch_scc0 .LBB0_381
	v_readlane_b32 s16, v247, 46
	v_ashrrev_i32_e32 v159, 31, v158
	v_readlane_b32 s17, v247, 47
	v_lshl_or_b32 v0, s66, 8, v152
	v_ashrrev_i32_e32 v1, 31, v0
	v_lshl_add_u64 v[2:3], v[158:159], 2, s[16:17]
	global_load_dword v96, v[2:3], off
	v_lshlrev_b64 v[4:5], 11, v[158:159]
	v_readlane_b32 s16, v249, 23
	v_lshl_add_u64 v[4:5], v[4:5], 0, v[0:1]
	v_readlane_b32 s17, v249, 24
	s_nop 1
	v_lshl_add_u64 v[6:7], v[4:5], 1, s[16:17]
	global_load_dwordx4 v[98:101], v[6:7], off
	v_lshl_add_u64 v[4:5], v[4:5], 2, s[88:89]
	global_load_dwordx4 v[164:167], v[4:5], off
	global_load_dwordx4 v[168:171], v[4:5], off offset:16
	s_waitcnt vmcnt(0)
	v_fmamk_f32 v96, v96, 0x3a000000, v189
	v_mul_f32_e32 v102, 0x4b800000, v96
	v_cmp_gt_f32_e32 vcc, s2, v96
	v_and_b32_e32 v103, 0xffff0000, v98
	s_nop 0
	v_cndmask_b32_e32 v96, v96, v102, vcc
	v_rsq_f32_e32 v96, v96
	v_lshlrev_b32_e32 v102, 16, v98
	v_lshlrev_b32_e32 v160, 16, v99
	v_and_b32_e32 v161, 0xffff0000, v99
	v_mul_f32_e32 v98, 0x45800000, v96
	v_cndmask_b32_e32 v176, v96, v98, vcc
	v_lshlrev_b32_e32 v172, 16, v100
	v_and_b32_e32 v173, 0xffff0000, v100
	v_lshlrev_b32_e32 v174, 16, v101
	v_and_b32_e32 v175, 0xffff0000, v101
	v_pk_mul_f32 v[98:99], v[142:143], v[176:177] op_sel_hi:[1,0]
	v_pk_mul_f32 v[100:101], v[140:141], v[176:177] op_sel_hi:[1,0]
	v_pk_mul_f32 v[186:187], v[138:139], v[176:177] op_sel_hi:[1,0]
	v_pk_mul_f32 v[198:199], v[136:137], v[176:177] op_sel_hi:[1,0]
	v_mul_f32_e32 v96, 0xbfb8aa3b, v100
	v_mul_f32_e32 v100, 0xbfb8aa3b, v101
	v_mul_f32_e32 v98, 0xbfb8aa3b, v98
	v_mul_f32_e32 v99, 0xbfb8aa3b, v99
	v_mul_f32_e32 v101, 0xbfb8aa3b, v198
	v_mul_f32_e32 v177, 0xbfb8aa3b, v199
	v_mul_f32_e32 v186, 0xbfb8aa3b, v186
	v_mul_f32_e32 v187, 0xbfb8aa3b, v187
	v_exp_f32_e32 v96, v96
	v_exp_f32_e32 v100, v100
	v_exp_f32_e32 v98, v98
	v_exp_f32_e32 v99, v99
	v_exp_f32_e32 v101, v101
	v_exp_f32_e32 v177, v177
	v_exp_f32_e32 v186, v186
	v_exp_f32_e32 v187, v187
	v_add_f32_e32 v96, 1.0, v96
	v_add_f32_e32 v100, 1.0, v100
	v_add_f32_e32 v198, 1.0, v98
	v_add_f32_e32 v199, 1.0, v99
	v_add_f32_e32 v200, 1.0, v101
	v_add_f32_e32 v177, 1.0, v177
	v_add_f32_e32 v201, 1.0, v186
	v_add_f32_e32 v202, 1.0, v187
	v_rcp_f32_e32 v98, v96
	v_rcp_f32_e32 v99, v100
	v_rcp_f32_e32 v100, v198
	v_rcp_f32_e32 v101, v199
	v_rcp_f32_e32 v186, v200
	v_rcp_f32_e32 v187, v177
	v_rcp_f32_e32 v198, v201
	v_rcp_f32_e32 v199, v202
	v_pk_fma_f32 v[98:99], v[98:99], v[102:103], v[164:165]
	v_pk_fma_f32 v[100:101], v[100:101], v[160:161], v[166:167]
	v_pk_fma_f32 v[164:165], v[186:187], v[172:173], v[168:169]
	v_pk_fma_f32 v[166:167], v[198:199], v[174:175], v[170:171]
	global_store_dwordx4 v[4:5], v[98:101], off
	global_store_dwordx4 v[4:5], v[164:167], off offset:16
	global_load_dwordx4 v[168:171], v[6:7], off offset:256
	global_load_dwordx4 v[172:175], v[4:5], off offset:512
	global_load_dwordx4 v[198:201], v[4:5], off offset:528
	v_and_b32_e32 v7, 64, v196
	v_xor_b32_e32 v6, 16, v196
	v_add_u32_e32 v202, 64, v7
	v_cmp_lt_i32_e32 vcc, v6, v202
	v_pk_mul_f32 v[102:103], v[68:69], v[176:177] op_sel_hi:[1,0]
	v_pk_mul_f32 v[160:161], v[66:67], v[176:177] op_sel_hi:[1,0]
	v_cndmask_b32_e32 v6, v196, v6, vcc
	v_lshlrev_b32_e32 v96, 2, v6
	v_pk_mul_f32 v[6:7], v[70:71], v[176:177] op_sel_hi:[1,0]
	v_mul_f32_e32 v102, 0xbfb8aa3b, v102
	v_mul_f32_e32 v103, 0xbfb8aa3b, v103
	v_mul_f32_e32 v6, 0xbfb8aa3b, v6
	v_mul_f32_e32 v7, 0xbfb8aa3b, v7
	v_exp_f32_e32 v102, v102
	v_exp_f32_e32 v103, v103
	v_pk_mul_f32 v[176:177], v[64:65], v[176:177] op_sel_hi:[1,0]
	v_exp_f32_e32 v6, v6
	v_exp_f32_e32 v7, v7
	v_mul_f32_e32 v176, 0xbfb8aa3b, v176
	v_mul_f32_e32 v177, 0xbfb8aa3b, v177
	v_pk_mul_f32 v[98:99], v[98:99], v[98:99]
	v_mul_f32_e32 v160, 0xbfb8aa3b, v160
	v_mul_f32_e32 v161, 0xbfb8aa3b, v161
	v_exp_f32_e32 v176, v176
	v_exp_f32_e32 v177, v177
	v_pk_mul_f32 v[100:101], v[100:101], v[100:101]
	v_add_f32_e32 v98, v98, v99
	v_exp_f32_e32 v160, v160
	v_exp_f32_e32 v161, v161
	v_add_f32_e32 v102, 1.0, v102
	v_add_f32_e32 v103, 1.0, v103
	v_add_f32_e32 v98, v100, v98
	v_add_f32_e32 v186, 1.0, v6
	v_add_f32_e32 v187, 1.0, v7
	v_rcp_f32_e32 v6, v102
	v_rcp_f32_e32 v7, v103
	v_pk_mul_f32 v[164:165], v[164:165], v[164:165]
	v_add_f32_e32 v98, v101, v98
	v_rcp_f32_e32 v102, v186
	v_rcp_f32_e32 v103, v187
	v_add_f32_e32 v98, v164, v98
	v_add_f32_e32 v176, 1.0, v176
	v_add_f32_e32 v177, 1.0, v177
	v_pk_mul_f32 v[186:187], v[166:167], v[166:167]
	v_add_f32_e32 v98, v165, v98
	v_add_f32_e32 v203, 1.0, v160
	v_add_f32_e32 v204, 1.0, v161
	v_rcp_f32_e32 v160, v176
	v_rcp_f32_e32 v161, v177
	v_add_f32_e32 v186, v186, v98
	v_rcp_f32_e32 v176, v203
	v_rcp_f32_e32 v177, v204
	s_waitcnt vmcnt(2)
	v_lshlrev_b32_e32 v98, 16, v168
	v_and_b32_e32 v99, 0xffff0000, v168
	v_lshlrev_b32_e32 v164, 16, v169
	v_and_b32_e32 v165, 0xffff0000, v169
	s_waitcnt vmcnt(1)
	v_pk_fma_f32 v[100:101], v[6:7], v[98:99], v[172:173]
	v_pk_fma_f32 v[102:103], v[102:103], v[164:165], v[174:175]
	v_pk_mul_f32 v[6:7], v[100:101], v[100:101]
	v_lshlrev_b32_e32 v166, 16, v170
	v_and_b32_e32 v167, 0xffff0000, v170
	v_pk_mul_f32 v[98:99], v[102:103], v[102:103]
	v_add_f32_e32 v6, v6, v7
	s_waitcnt vmcnt(0)
	v_pk_fma_f32 v[164:165], v[160:161], v[166:167], v[198:199]
	v_add_f32_e32 v6, v98, v6
	v_lshlrev_b32_e32 v168, 16, v171
	v_and_b32_e32 v169, 0xffff0000, v171
	v_pk_mul_f32 v[160:161], v[164:165], v[164:165]
	v_add_f32_e32 v6, v99, v6
	v_pk_fma_f32 v[166:167], v[176:177], v[168:169], v[200:201]
	v_add_f32_e32 v6, v160, v6
	v_pk_mul_f32 v[168:169], v[166:167], v[166:167]
	v_add_f32_e32 v6, v161, v6
	v_add_f32_e32 v6, v168, v6
	v_add_f32_e32 v170, v187, v186
	v_add_f32_e32 v6, v169, v6
	v_add_f32_e32 v6, v170, v6
	ds_bpermute_b32 v7, v96, v6
	v_xor_b32_e32 v98, 32, v196
	v_cmp_lt_i32_e32 vcc, v98, v202
	global_store_dwordx4 v[4:5], v[100:103], off offset:512
	global_store_dwordx4 v[4:5], v[164:167], off offset:528
	v_cndmask_b32_e32 v98, v196, v98, vcc
	v_lshlrev_b32_e32 v98, 2, v98
	s_waitcnt lgkmcnt(0)
	v_add_f32_e32 v6, v6, v7
	ds_bpermute_b32 v7, v98, v6
	s_and_saveexec_b64 s[26:27], s[36:37]
	s_cbranch_execz .LBB0_366
	v_readlane_b32 s16, v247, 48
	v_readlane_b32 s17, v247, 49
	s_waitcnt lgkmcnt(0)
	v_add_f32_e32 v6, v6, v7
	v_lshl_add_u64 v[4:5], v[158:159], 2, s[16:17]
	v_mov_b32_e32 v216, v6
.LBB0_366:
	s_or_b64 exec, exec, s[26:27]
	v_or_b32_e32 v4, 16, v158
	v_readlane_b32 s16, v247, 46
	v_ashrrev_i32_e32 v5, 31, v4
	v_readlane_b32 s17, v247, 47
	s_waitcnt lgkmcnt(0)
	s_nop 0
	v_lshl_add_u64 v[6:7], v[4:5], 2, s[16:17]
	global_load_dword v99, v[6:7], off
	v_lshlrev_b64 v[6:7], 11, v[4:5]
	v_readlane_b32 s16, v249, 23
	v_lshl_add_u64 v[6:7], v[6:7], 0, v[0:1]
	v_readlane_b32 s17, v249, 24
	s_waitcnt vmcnt(0)
	v_fmamk_f32 v99, v99, 0x3a000000, v189
	v_lshl_add_u64 v[160:161], v[6:7], 1, s[16:17]
	global_load_dwordx4 v[100:103], v[160:161], off
	v_lshl_add_u64 v[6:7], v[6:7], 2, s[88:89]
	global_load_dwordx4 v[164:167], v[6:7], off
	global_load_dwordx4 v[168:171], v[6:7], off offset:16
	v_mul_f32_e32 v159, 0x4b800000, v99
	v_cmp_gt_f32_e32 vcc, s2, v99
	s_waitcnt vmcnt(2)
	v_lshlrev_b32_e32 v172, 16, v100
	v_cndmask_b32_e32 v99, v99, v159, vcc
	v_rsq_f32_e32 v99, v99
	v_and_b32_e32 v173, 0xffff0000, v100
	v_lshlrev_b32_e32 v174, 16, v101
	v_and_b32_e32 v175, 0xffff0000, v101
	v_mul_f32_e32 v100, 0x45800000, v99
	v_cndmask_b32_e32 v202, v99, v100, vcc
	v_lshlrev_b32_e32 v176, 16, v102
	v_and_b32_e32 v177, 0xffff0000, v102
	v_lshlrev_b32_e32 v186, 16, v103
	v_and_b32_e32 v187, 0xffff0000, v103
	v_pk_mul_f32 v[100:101], v[134:135], v[202:203] op_sel_hi:[1,0]
	v_pk_mul_f32 v[102:103], v[132:133], v[202:203] op_sel_hi:[1,0]
	v_pk_mul_f32 v[198:199], v[130:131], v[202:203] op_sel_hi:[1,0]
	v_pk_mul_f32 v[200:201], v[128:129], v[202:203] op_sel_hi:[1,0]
	v_mul_f32_e32 v99, 0xbfb8aa3b, v102
	v_mul_f32_e32 v102, 0xbfb8aa3b, v103
	v_mul_f32_e32 v100, 0xbfb8aa3b, v100
	v_mul_f32_e32 v101, 0xbfb8aa3b, v101
	v_mul_f32_e32 v103, 0xbfb8aa3b, v200
	v_mul_f32_e32 v159, 0xbfb8aa3b, v201
	v_mul_f32_e32 v198, 0xbfb8aa3b, v198
	v_mul_f32_e32 v199, 0xbfb8aa3b, v199
	v_exp_f32_e32 v99, v99
	v_exp_f32_e32 v102, v102
	v_exp_f32_e32 v100, v100
	v_exp_f32_e32 v101, v101
	v_exp_f32_e32 v103, v103
	v_exp_f32_e32 v159, v159
	v_exp_f32_e32 v198, v198
	v_exp_f32_e32 v199, v199
	v_add_f32_e32 v99, 1.0, v99
	v_add_f32_e32 v102, 1.0, v102
	v_add_f32_e32 v200, 1.0, v100
	v_add_f32_e32 v201, 1.0, v101
	v_add_f32_e32 v203, 1.0, v103
	v_add_f32_e32 v159, 1.0, v159
	v_add_f32_e32 v204, 1.0, v198
	v_add_f32_e32 v205, 1.0, v199
	v_rcp_f32_e32 v100, v99
	v_rcp_f32_e32 v101, v102
	v_rcp_f32_e32 v102, v200
	v_rcp_f32_e32 v103, v201
	v_rcp_f32_e32 v198, v203
	v_rcp_f32_e32 v199, v159
	v_rcp_f32_e32 v200, v204
	v_rcp_f32_e32 v201, v205
	s_waitcnt vmcnt(1)
	v_pk_fma_f32 v[100:101], v[100:101], v[172:173], v[164:165]
	v_pk_fma_f32 v[102:103], v[102:103], v[174:175], v[166:167]
	s_waitcnt vmcnt(0)
	v_pk_fma_f32 v[164:165], v[198:199], v[176:177], v[168:169]
	v_pk_fma_f32 v[166:167], v[200:201], v[186:187], v[170:171]
	global_store_dwordx4 v[6:7], v[100:103], off
	global_store_dwordx4 v[6:7], v[164:167], off offset:16
	global_load_dwordx4 v[168:171], v[160:161], off offset:256
	global_load_dwordx4 v[172:175], v[6:7], off offset:512
	global_load_dwordx4 v[198:201], v[6:7], off offset:528
	v_pk_mul_f32 v[176:177], v[60:61], v[202:203] op_sel_hi:[1,0]
	v_pk_mul_f32 v[160:161], v[62:63], v[202:203] op_sel_hi:[1,0]
	v_mul_f32_e32 v99, 0xbfb8aa3b, v176
	v_mul_f32_e32 v159, 0xbfb8aa3b, v177
	v_pk_mul_f32 v[186:187], v[58:59], v[202:203] op_sel_hi:[1,0]
	v_pk_mul_f32 v[202:203], v[56:57], v[202:203] op_sel_hi:[1,0]
	v_mul_f32_e32 v160, 0xbfb8aa3b, v160
	v_mul_f32_e32 v161, 0xbfb8aa3b, v161
	v_exp_f32_e32 v99, v99
	v_exp_f32_e32 v159, v159
	v_mul_f32_e32 v176, 0xbfb8aa3b, v202
	v_mul_f32_e32 v177, 0xbfb8aa3b, v203
	v_exp_f32_e32 v160, v160
	v_exp_f32_e32 v161, v161
	v_exp_f32_e32 v176, v176
	v_exp_f32_e32 v177, v177
	v_mul_f32_e32 v186, 0xbfb8aa3b, v186
	v_mul_f32_e32 v187, 0xbfb8aa3b, v187
	v_exp_f32_e32 v186, v186
	v_exp_f32_e32 v187, v187
	v_add_f32_e32 v99, 1.0, v99
	v_add_f32_e32 v159, 1.0, v159
	v_pk_mul_f32 v[100:101], v[100:101], v[100:101]
	v_add_f32_e32 v202, 1.0, v160
	v_add_f32_e32 v203, 1.0, v161
	v_rcp_f32_e32 v160, v99
	v_rcp_f32_e32 v161, v159
	v_pk_mul_f32 v[102:103], v[102:103], v[102:103]
	v_add_f32_e32 v99, v100, v101
	v_add_f32_e32 v204, 1.0, v176
	v_add_f32_e32 v205, 1.0, v177
	v_rcp_f32_e32 v176, v202
	v_rcp_f32_e32 v177, v203
	v_add_f32_e32 v99, v102, v99
	v_pk_mul_f32 v[164:165], v[164:165], v[164:165]
	v_add_f32_e32 v99, v103, v99
	v_add_f32_e32 v206, 1.0, v186
	v_add_f32_e32 v207, 1.0, v187
	v_rcp_f32_e32 v186, v204
	v_rcp_f32_e32 v187, v205
	v_add_f32_e32 v99, v164, v99
	v_add_f32_e32 v99, v165, v99
	v_rcp_f32_e32 v202, v206
	v_rcp_f32_e32 v203, v207
	v_pk_mul_f32 v[204:205], v[166:167], v[166:167]
	s_waitcnt vmcnt(2)
	v_lshlrev_b32_e32 v100, 16, v168
	v_and_b32_e32 v101, 0xffff0000, v168
	v_lshlrev_b32_e32 v102, 16, v169
	v_and_b32_e32 v103, 0xffff0000, v169
	s_waitcnt vmcnt(1)
	v_pk_fma_f32 v[164:165], v[160:161], v[100:101], v[172:173]
	v_pk_fma_f32 v[166:167], v[176:177], v[102:103], v[174:175]
	v_pk_mul_f32 v[100:101], v[164:165], v[164:165]
	v_lshlrev_b32_e32 v168, 16, v170
	v_and_b32_e32 v169, 0xffff0000, v170
	v_pk_mul_f32 v[102:103], v[166:167], v[166:167]
	v_add_f32_e32 v100, v100, v101
	s_waitcnt vmcnt(0)
	v_pk_fma_f32 v[168:169], v[186:187], v[168:169], v[198:199]
	v_add_f32_e32 v100, v102, v100
	v_lshlrev_b32_e32 v170, 16, v171
	v_and_b32_e32 v171, 0xffff0000, v171
	v_pk_mul_f32 v[160:161], v[168:169], v[168:169]
	v_add_f32_e32 v100, v103, v100
	v_pk_fma_f32 v[170:171], v[202:203], v[170:171], v[200:201]
	v_add_f32_e32 v100, v160, v100
	v_pk_mul_f32 v[172:173], v[170:171], v[170:171]
	v_add_f32_e32 v100, v161, v100
	v_add_f32_e32 v99, v204, v99
	v_add_f32_e32 v100, v172, v100
	v_add_f32_e32 v99, v205, v99
	v_add_f32_e32 v100, v173, v100
	v_add_f32_e32 v99, v99, v100
	ds_bpermute_b32 v100, v96, v99
	global_store_dwordx4 v[6:7], v[164:167], off offset:512
	global_store_dwordx4 v[6:7], v[168:171], off offset:528
	s_waitcnt lgkmcnt(0)
	v_add_f32_e32 v99, v99, v100
	ds_bpermute_b32 v100, v98, v99
	s_and_saveexec_b64 s[26:27], s[36:37]
	s_cbranch_execz .LBB0_368
	v_readlane_b32 s16, v247, 48
	v_readlane_b32 s17, v247, 49
	s_waitcnt lgkmcnt(0)
	v_add_f32_e32 v6, v99, v100
	v_lshl_add_u64 v[4:5], v[4:5], 2, s[16:17]
	v_mov_b32_e32 v217, v6
.LBB0_368:
	s_or_b64 exec, exec, s[26:27]
	v_or_b32_e32 v4, 32, v158
	v_readlane_b32 s16, v247, 46
	v_ashrrev_i32_e32 v5, 31, v4
	v_readlane_b32 s17, v247, 47
	s_nop 1
	v_lshl_add_u64 v[6:7], v[4:5], 2, s[16:17]
	global_load_dword v99, v[6:7], off
	v_lshlrev_b64 v[6:7], 11, v[4:5]
	v_readlane_b32 s16, v249, 23
	v_lshl_add_u64 v[6:7], v[6:7], 0, v[0:1]
	v_readlane_b32 s17, v249, 24
	s_waitcnt vmcnt(0)
	v_fmamk_f32 v99, v99, 0x3a000000, v189
	v_lshl_add_u64 v[160:161], v[6:7], 1, s[16:17]
	s_waitcnt lgkmcnt(0)
	global_load_dwordx4 v[100:103], v[160:161], off
	v_lshl_add_u64 v[6:7], v[6:7], 2, s[88:89]
	global_load_dwordx4 v[164:167], v[6:7], off
	global_load_dwordx4 v[168:171], v[6:7], off offset:16
	v_mul_f32_e32 v159, 0x4b800000, v99
	v_cmp_gt_f32_e32 vcc, s2, v99
	s_waitcnt vmcnt(2)
	v_lshlrev_b32_e32 v172, 16, v100
	v_cndmask_b32_e32 v99, v99, v159, vcc
	v_rsq_f32_e32 v99, v99
	v_and_b32_e32 v173, 0xffff0000, v100
	v_lshlrev_b32_e32 v174, 16, v101
	v_and_b32_e32 v175, 0xffff0000, v101
	v_mul_f32_e32 v100, 0x45800000, v99
	v_cndmask_b32_e32 v202, v99, v100, vcc
	v_lshlrev_b32_e32 v176, 16, v102
	v_and_b32_e32 v177, 0xffff0000, v102
	v_lshlrev_b32_e32 v186, 16, v103
	v_and_b32_e32 v187, 0xffff0000, v103
	v_pk_mul_f32 v[100:101], v[126:127], v[202:203] op_sel_hi:[1,0]
	v_pk_mul_f32 v[102:103], v[124:125], v[202:203] op_sel_hi:[1,0]
	v_pk_mul_f32 v[198:199], v[122:123], v[202:203] op_sel_hi:[1,0]
	v_pk_mul_f32 v[200:201], v[120:121], v[202:203] op_sel_hi:[1,0]
	v_mul_f32_e32 v99, 0xbfb8aa3b, v102
	v_mul_f32_e32 v102, 0xbfb8aa3b, v103
	v_mul_f32_e32 v100, 0xbfb8aa3b, v100
	v_mul_f32_e32 v101, 0xbfb8aa3b, v101
	v_mul_f32_e32 v103, 0xbfb8aa3b, v200
	v_mul_f32_e32 v159, 0xbfb8aa3b, v201
	v_mul_f32_e32 v198, 0xbfb8aa3b, v198
	v_mul_f32_e32 v199, 0xbfb8aa3b, v199
	v_exp_f32_e32 v99, v99
	v_exp_f32_e32 v102, v102
	v_exp_f32_e32 v100, v100
	v_exp_f32_e32 v101, v101
	v_exp_f32_e32 v103, v103
	v_exp_f32_e32 v159, v159
	v_exp_f32_e32 v198, v198
	v_exp_f32_e32 v199, v199
	v_add_f32_e32 v99, 1.0, v99
	v_add_f32_e32 v102, 1.0, v102
	v_add_f32_e32 v200, 1.0, v100
	v_add_f32_e32 v201, 1.0, v101
	v_add_f32_e32 v203, 1.0, v103
	v_add_f32_e32 v159, 1.0, v159
	v_add_f32_e32 v204, 1.0, v198
	v_add_f32_e32 v205, 1.0, v199
	v_rcp_f32_e32 v100, v99
	v_rcp_f32_e32 v101, v102
	v_rcp_f32_e32 v102, v200
	v_rcp_f32_e32 v103, v201
	v_rcp_f32_e32 v198, v203
	v_rcp_f32_e32 v199, v159
	v_rcp_f32_e32 v200, v204
	v_rcp_f32_e32 v201, v205
	s_waitcnt vmcnt(1)
	v_pk_fma_f32 v[100:101], v[100:101], v[172:173], v[164:165]
	v_pk_fma_f32 v[102:103], v[102:103], v[174:175], v[166:167]
	s_waitcnt vmcnt(0)
	v_pk_fma_f32 v[164:165], v[198:199], v[176:177], v[168:169]
	v_pk_fma_f32 v[166:167], v[200:201], v[186:187], v[170:171]
	global_store_dwordx4 v[6:7], v[100:103], off
	global_store_dwordx4 v[6:7], v[164:167], off offset:16
	global_load_dwordx4 v[168:171], v[160:161], off offset:256
	global_load_dwordx4 v[172:175], v[6:7], off offset:512
	global_load_dwordx4 v[198:201], v[6:7], off offset:528
	v_pk_mul_f32 v[176:177], v[52:53], v[202:203] op_sel_hi:[1,0]
	v_pk_mul_f32 v[160:161], v[54:55], v[202:203] op_sel_hi:[1,0]
	v_mul_f32_e32 v99, 0xbfb8aa3b, v176
	v_mul_f32_e32 v159, 0xbfb8aa3b, v177
	v_pk_mul_f32 v[186:187], v[50:51], v[202:203] op_sel_hi:[1,0]
	v_pk_mul_f32 v[202:203], v[48:49], v[202:203] op_sel_hi:[1,0]
	v_mul_f32_e32 v160, 0xbfb8aa3b, v160
	v_mul_f32_e32 v161, 0xbfb8aa3b, v161
	v_exp_f32_e32 v99, v99
	v_exp_f32_e32 v159, v159
	v_mul_f32_e32 v176, 0xbfb8aa3b, v202
	v_mul_f32_e32 v177, 0xbfb8aa3b, v203
	v_exp_f32_e32 v160, v160
	v_exp_f32_e32 v161, v161
	v_exp_f32_e32 v176, v176
	v_exp_f32_e32 v177, v177
	v_mul_f32_e32 v186, 0xbfb8aa3b, v186
	v_mul_f32_e32 v187, 0xbfb8aa3b, v187
	v_exp_f32_e32 v186, v186
	v_exp_f32_e32 v187, v187
	v_add_f32_e32 v99, 1.0, v99
	v_add_f32_e32 v159, 1.0, v159
	v_pk_mul_f32 v[100:101], v[100:101], v[100:101]
	v_add_f32_e32 v202, 1.0, v160
	v_add_f32_e32 v203, 1.0, v161
	v_rcp_f32_e32 v160, v99
	v_rcp_f32_e32 v161, v159
	v_pk_mul_f32 v[102:103], v[102:103], v[102:103]
	v_add_f32_e32 v99, v100, v101
	v_add_f32_e32 v204, 1.0, v176
	v_add_f32_e32 v205, 1.0, v177
	v_rcp_f32_e32 v176, v202
	v_rcp_f32_e32 v177, v203
	v_add_f32_e32 v99, v102, v99
	v_pk_mul_f32 v[164:165], v[164:165], v[164:165]
	v_add_f32_e32 v99, v103, v99
	v_add_f32_e32 v206, 1.0, v186
	v_add_f32_e32 v207, 1.0, v187
	v_rcp_f32_e32 v186, v204
	v_rcp_f32_e32 v187, v205
	v_add_f32_e32 v99, v164, v99
	v_add_f32_e32 v99, v165, v99
	v_rcp_f32_e32 v202, v206
	v_rcp_f32_e32 v203, v207
	v_pk_mul_f32 v[204:205], v[166:167], v[166:167]
	s_waitcnt vmcnt(2)
	v_lshlrev_b32_e32 v100, 16, v168
	v_and_b32_e32 v101, 0xffff0000, v168
	v_lshlrev_b32_e32 v102, 16, v169
	v_and_b32_e32 v103, 0xffff0000, v169
	s_waitcnt vmcnt(1)
	v_pk_fma_f32 v[164:165], v[160:161], v[100:101], v[172:173]
	v_pk_fma_f32 v[166:167], v[176:177], v[102:103], v[174:175]
	v_pk_mul_f32 v[100:101], v[164:165], v[164:165]
	v_lshlrev_b32_e32 v168, 16, v170
	v_and_b32_e32 v169, 0xffff0000, v170
	v_pk_mul_f32 v[102:103], v[166:167], v[166:167]
	v_add_f32_e32 v100, v100, v101
	s_waitcnt vmcnt(0)
	v_pk_fma_f32 v[168:169], v[186:187], v[168:169], v[198:199]
	v_add_f32_e32 v100, v102, v100
	v_lshlrev_b32_e32 v170, 16, v171
	v_and_b32_e32 v171, 0xffff0000, v171
	v_pk_mul_f32 v[160:161], v[168:169], v[168:169]
	v_add_f32_e32 v100, v103, v100
	v_pk_fma_f32 v[170:171], v[202:203], v[170:171], v[200:201]
	v_add_f32_e32 v100, v160, v100
	v_pk_mul_f32 v[172:173], v[170:171], v[170:171]
	v_add_f32_e32 v100, v161, v100
	v_add_f32_e32 v99, v204, v99
	v_add_f32_e32 v100, v172, v100
	v_add_f32_e32 v99, v205, v99
	v_add_f32_e32 v100, v173, v100
	v_add_f32_e32 v99, v99, v100
	ds_bpermute_b32 v100, v96, v99
	global_store_dwordx4 v[6:7], v[164:167], off offset:512
	global_store_dwordx4 v[6:7], v[168:171], off offset:528
	s_waitcnt lgkmcnt(0)
	v_add_f32_e32 v99, v99, v100
	ds_bpermute_b32 v100, v98, v99
	s_and_saveexec_b64 s[26:27], s[36:37]
	s_cbranch_execz .LBB0_370
	v_readlane_b32 s16, v247, 48
	v_readlane_b32 s17, v247, 49
	s_waitcnt lgkmcnt(0)
	v_add_f32_e32 v6, v99, v100
	v_lshl_add_u64 v[4:5], v[4:5], 2, s[16:17]
	v_mov_b32_e32 v218, v6
.LBB0_370:
	s_or_b64 exec, exec, s[26:27]
	v_or_b32_e32 v4, 48, v158
	v_readlane_b32 s16, v247, 46
	v_ashrrev_i32_e32 v5, 31, v4
	v_readlane_b32 s17, v247, 47
	s_nop 1
	v_lshl_add_u64 v[6:7], v[4:5], 2, s[16:17]
	global_load_dword v99, v[6:7], off
	v_lshlrev_b64 v[6:7], 11, v[4:5]
	v_readlane_b32 s16, v249, 23
	v_lshl_add_u64 v[6:7], v[6:7], 0, v[0:1]
	v_readlane_b32 s17, v249, 24
	s_waitcnt vmcnt(0)
	v_fmamk_f32 v99, v99, 0x3a000000, v189
	v_lshl_add_u64 v[160:161], v[6:7], 1, s[16:17]
	s_waitcnt lgkmcnt(0)
	global_load_dwordx4 v[100:103], v[160:161], off
	v_lshl_add_u64 v[6:7], v[6:7], 2, s[88:89]
	global_load_dwordx4 v[164:167], v[6:7], off
	global_load_dwordx4 v[168:171], v[6:7], off offset:16
	v_mul_f32_e32 v159, 0x4b800000, v99
	v_cmp_gt_f32_e32 vcc, s2, v99
	s_waitcnt vmcnt(2)
	v_lshlrev_b32_e32 v172, 16, v100
	v_cndmask_b32_e32 v99, v99, v159, vcc
	v_rsq_f32_e32 v99, v99
	v_and_b32_e32 v173, 0xffff0000, v100
	v_lshlrev_b32_e32 v174, 16, v101
	v_and_b32_e32 v175, 0xffff0000, v101
	v_mul_f32_e32 v100, 0x45800000, v99
	v_cndmask_b32_e32 v202, v99, v100, vcc
	v_lshlrev_b32_e32 v176, 16, v102
	v_and_b32_e32 v177, 0xffff0000, v102
	v_lshlrev_b32_e32 v186, 16, v103
	v_and_b32_e32 v187, 0xffff0000, v103
	v_pk_mul_f32 v[100:101], v[118:119], v[202:203] op_sel_hi:[1,0]
	v_pk_mul_f32 v[102:103], v[116:117], v[202:203] op_sel_hi:[1,0]
	v_pk_mul_f32 v[198:199], v[114:115], v[202:203] op_sel_hi:[1,0]
	v_pk_mul_f32 v[200:201], v[112:113], v[202:203] op_sel_hi:[1,0]
	v_mul_f32_e32 v99, 0xbfb8aa3b, v102
	v_mul_f32_e32 v102, 0xbfb8aa3b, v103
	v_mul_f32_e32 v100, 0xbfb8aa3b, v100
	v_mul_f32_e32 v101, 0xbfb8aa3b, v101
	v_mul_f32_e32 v103, 0xbfb8aa3b, v200
	v_mul_f32_e32 v159, 0xbfb8aa3b, v201
	v_mul_f32_e32 v198, 0xbfb8aa3b, v198
	v_mul_f32_e32 v199, 0xbfb8aa3b, v199
	v_exp_f32_e32 v99, v99
	v_exp_f32_e32 v102, v102
	v_exp_f32_e32 v100, v100
	v_exp_f32_e32 v101, v101
	v_exp_f32_e32 v103, v103
	v_exp_f32_e32 v159, v159
	v_exp_f32_e32 v198, v198
	v_exp_f32_e32 v199, v199
	v_add_f32_e32 v99, 1.0, v99
	v_add_f32_e32 v102, 1.0, v102
	v_add_f32_e32 v200, 1.0, v100
	v_add_f32_e32 v201, 1.0, v101
	v_add_f32_e32 v203, 1.0, v103
	v_add_f32_e32 v159, 1.0, v159
	v_add_f32_e32 v204, 1.0, v198
	v_add_f32_e32 v205, 1.0, v199
	v_rcp_f32_e32 v100, v99
	v_rcp_f32_e32 v101, v102
	v_rcp_f32_e32 v102, v200
	v_rcp_f32_e32 v103, v201
	v_rcp_f32_e32 v198, v203
	v_rcp_f32_e32 v199, v159
	v_rcp_f32_e32 v200, v204
	v_rcp_f32_e32 v201, v205
	s_waitcnt vmcnt(1)
	v_pk_fma_f32 v[100:101], v[100:101], v[172:173], v[164:165]
	v_pk_fma_f32 v[102:103], v[102:103], v[174:175], v[166:167]
	s_waitcnt vmcnt(0)
	v_pk_fma_f32 v[164:165], v[198:199], v[176:177], v[168:169]
	v_pk_fma_f32 v[166:167], v[200:201], v[186:187], v[170:171]
	global_store_dwordx4 v[6:7], v[100:103], off
	global_store_dwordx4 v[6:7], v[164:167], off offset:16
	global_load_dwordx4 v[168:171], v[160:161], off offset:256
	global_load_dwordx4 v[172:175], v[6:7], off offset:512
	global_load_dwordx4 v[198:201], v[6:7], off offset:528
	v_pk_mul_f32 v[176:177], v[44:45], v[202:203] op_sel_hi:[1,0]
	v_pk_mul_f32 v[160:161], v[46:47], v[202:203] op_sel_hi:[1,0]
	v_mul_f32_e32 v99, 0xbfb8aa3b, v176
	v_mul_f32_e32 v159, 0xbfb8aa3b, v177
	v_pk_mul_f32 v[186:187], v[42:43], v[202:203] op_sel_hi:[1,0]
	v_pk_mul_f32 v[202:203], v[40:41], v[202:203] op_sel_hi:[1,0]
	v_mul_f32_e32 v160, 0xbfb8aa3b, v160
	v_mul_f32_e32 v161, 0xbfb8aa3b, v161
	v_exp_f32_e32 v99, v99
	v_exp_f32_e32 v159, v159
	v_mul_f32_e32 v176, 0xbfb8aa3b, v202
	v_mul_f32_e32 v177, 0xbfb8aa3b, v203
	v_exp_f32_e32 v160, v160
	v_exp_f32_e32 v161, v161
	v_exp_f32_e32 v176, v176
	v_exp_f32_e32 v177, v177
	v_mul_f32_e32 v186, 0xbfb8aa3b, v186
	v_mul_f32_e32 v187, 0xbfb8aa3b, v187
	v_exp_f32_e32 v186, v186
	v_exp_f32_e32 v187, v187
	v_add_f32_e32 v99, 1.0, v99
	v_add_f32_e32 v159, 1.0, v159
	v_pk_mul_f32 v[100:101], v[100:101], v[100:101]
	v_add_f32_e32 v202, 1.0, v160
	v_add_f32_e32 v203, 1.0, v161
	v_rcp_f32_e32 v160, v99
	v_rcp_f32_e32 v161, v159
	v_pk_mul_f32 v[102:103], v[102:103], v[102:103]
	v_add_f32_e32 v99, v100, v101
	v_add_f32_e32 v204, 1.0, v176
	v_add_f32_e32 v205, 1.0, v177
	v_rcp_f32_e32 v176, v202
	v_rcp_f32_e32 v177, v203
	v_add_f32_e32 v99, v102, v99
	v_pk_mul_f32 v[164:165], v[164:165], v[164:165]
	v_add_f32_e32 v99, v103, v99
	v_add_f32_e32 v206, 1.0, v186
	v_add_f32_e32 v207, 1.0, v187
	v_rcp_f32_e32 v186, v204
	v_rcp_f32_e32 v187, v205
	v_add_f32_e32 v99, v164, v99
	v_add_f32_e32 v99, v165, v99
	v_rcp_f32_e32 v202, v206
	v_rcp_f32_e32 v203, v207
	v_pk_mul_f32 v[204:205], v[166:167], v[166:167]
	s_waitcnt vmcnt(2)
	v_lshlrev_b32_e32 v100, 16, v168
	v_and_b32_e32 v101, 0xffff0000, v168
	v_lshlrev_b32_e32 v102, 16, v169
	v_and_b32_e32 v103, 0xffff0000, v169
	s_waitcnt vmcnt(1)
	v_pk_fma_f32 v[164:165], v[160:161], v[100:101], v[172:173]
	v_pk_fma_f32 v[166:167], v[176:177], v[102:103], v[174:175]
	v_pk_mul_f32 v[100:101], v[164:165], v[164:165]
	v_lshlrev_b32_e32 v168, 16, v170
	v_and_b32_e32 v169, 0xffff0000, v170
	v_pk_mul_f32 v[102:103], v[166:167], v[166:167]
	v_add_f32_e32 v100, v100, v101
	s_waitcnt vmcnt(0)
	v_pk_fma_f32 v[168:169], v[186:187], v[168:169], v[198:199]
	v_add_f32_e32 v100, v102, v100
	v_lshlrev_b32_e32 v170, 16, v171
	v_and_b32_e32 v171, 0xffff0000, v171
	v_pk_mul_f32 v[160:161], v[168:169], v[168:169]
	v_add_f32_e32 v100, v103, v100
	v_pk_fma_f32 v[170:171], v[202:203], v[170:171], v[200:201]
	v_add_f32_e32 v100, v160, v100
	v_pk_mul_f32 v[172:173], v[170:171], v[170:171]
	v_add_f32_e32 v100, v161, v100
	v_add_f32_e32 v99, v204, v99
	v_add_f32_e32 v100, v172, v100
	v_add_f32_e32 v99, v205, v99
	v_add_f32_e32 v100, v173, v100
	v_add_f32_e32 v99, v99, v100
	ds_bpermute_b32 v100, v96, v99
	global_store_dwordx4 v[6:7], v[164:167], off offset:512
	global_store_dwordx4 v[6:7], v[168:171], off offset:528
	s_waitcnt lgkmcnt(0)
	v_add_f32_e32 v99, v99, v100
	ds_bpermute_b32 v100, v98, v99
	s_and_saveexec_b64 s[26:27], s[36:37]
	s_cbranch_execz .LBB0_372
	v_readlane_b32 s16, v247, 48
	v_readlane_b32 s17, v247, 49
	s_waitcnt lgkmcnt(0)
	v_add_f32_e32 v6, v99, v100
	v_lshl_add_u64 v[4:5], v[4:5], 2, s[16:17]
	v_mov_b32_e32 v219, v6
.LBB0_372:
	s_or_b64 exec, exec, s[26:27]
	global_load_dword v99, v[2:3], off offset:512
	v_add_u32_e32 v4, 0x80, v158
	v_ashrrev_i32_e32 v5, 31, v4
	v_lshlrev_b64 v[6:7], 11, v[4:5]
	v_readlane_b32 s16, v249, 23
	v_lshl_add_u64 v[6:7], v[6:7], 0, v[0:1]
	v_readlane_b32 s17, v249, 24
	s_nop 1
	v_lshl_add_u64 v[160:161], v[6:7], 1, s[16:17]
	s_waitcnt lgkmcnt(0)
	global_load_dwordx4 v[100:103], v[160:161], off
	v_lshl_add_u64 v[6:7], v[6:7], 2, s[88:89]
	global_load_dwordx4 v[164:167], v[6:7], off
	global_load_dwordx4 v[168:171], v[6:7], off offset:16
	s_waitcnt vmcnt(3)
	v_fmamk_f32 v99, v99, 0x3a000000, v189
	v_mul_f32_e32 v159, 0x4b800000, v99
	v_cmp_gt_f32_e32 vcc, s2, v99
	s_waitcnt vmcnt(2)
	v_lshlrev_b32_e32 v172, 16, v100
	v_cndmask_b32_e32 v99, v99, v159, vcc
	v_rsq_f32_e32 v99, v99
	v_and_b32_e32 v173, 0xffff0000, v100
	v_lshlrev_b32_e32 v174, 16, v101
	v_and_b32_e32 v175, 0xffff0000, v101
	v_mul_f32_e32 v100, 0x45800000, v99
	v_cndmask_b32_e32 v202, v99, v100, vcc
	v_lshlrev_b32_e32 v176, 16, v102
	v_and_b32_e32 v177, 0xffff0000, v102
	v_lshlrev_b32_e32 v186, 16, v103
	v_and_b32_e32 v187, 0xffff0000, v103
	v_pk_mul_f32 v[100:101], v[110:111], v[202:203] op_sel_hi:[1,0]
	v_pk_mul_f32 v[102:103], v[108:109], v[202:203] op_sel_hi:[1,0]
	v_pk_mul_f32 v[198:199], v[106:107], v[202:203] op_sel_hi:[1,0]
	v_pk_mul_f32 v[200:201], v[104:105], v[202:203] op_sel_hi:[1,0]
	v_mul_f32_e32 v99, 0xbfb8aa3b, v102
	v_mul_f32_e32 v102, 0xbfb8aa3b, v103
	v_mul_f32_e32 v100, 0xbfb8aa3b, v100
	v_mul_f32_e32 v101, 0xbfb8aa3b, v101
	v_mul_f32_e32 v103, 0xbfb8aa3b, v200
	v_mul_f32_e32 v159, 0xbfb8aa3b, v201
	v_mul_f32_e32 v198, 0xbfb8aa3b, v198
	v_mul_f32_e32 v199, 0xbfb8aa3b, v199
	v_exp_f32_e32 v99, v99
	v_exp_f32_e32 v102, v102
	v_exp_f32_e32 v100, v100
	v_exp_f32_e32 v101, v101
	v_exp_f32_e32 v103, v103
	v_exp_f32_e32 v159, v159
	v_exp_f32_e32 v198, v198
	v_exp_f32_e32 v199, v199
	v_add_f32_e32 v99, 1.0, v99
	v_add_f32_e32 v102, 1.0, v102
	v_add_f32_e32 v200, 1.0, v100
	v_add_f32_e32 v201, 1.0, v101
	v_add_f32_e32 v203, 1.0, v103
	v_add_f32_e32 v159, 1.0, v159
	v_add_f32_e32 v204, 1.0, v198
	v_add_f32_e32 v205, 1.0, v199
	v_rcp_f32_e32 v100, v99
	v_rcp_f32_e32 v101, v102
	v_rcp_f32_e32 v102, v200
	v_rcp_f32_e32 v103, v201
	v_rcp_f32_e32 v198, v203
	v_rcp_f32_e32 v199, v159
	v_rcp_f32_e32 v200, v204
	v_rcp_f32_e32 v201, v205
	s_waitcnt vmcnt(1)
	v_pk_fma_f32 v[100:101], v[100:101], v[172:173], v[164:165]
	v_pk_fma_f32 v[102:103], v[102:103], v[174:175], v[166:167]
	s_waitcnt vmcnt(0)
	v_pk_fma_f32 v[164:165], v[198:199], v[176:177], v[168:169]
	v_pk_fma_f32 v[166:167], v[200:201], v[186:187], v[170:171]
	global_store_dwordx4 v[6:7], v[100:103], off
	global_store_dwordx4 v[6:7], v[164:167], off offset:16
	global_load_dwordx4 v[168:171], v[160:161], off offset:256
	global_load_dwordx4 v[172:175], v[6:7], off offset:512
	global_load_dwordx4 v[198:201], v[6:7], off offset:528
	v_pk_mul_f32 v[176:177], v[36:37], v[202:203] op_sel_hi:[1,0]
	v_pk_mul_f32 v[160:161], v[38:39], v[202:203] op_sel_hi:[1,0]
	v_mul_f32_e32 v99, 0xbfb8aa3b, v176
	v_mul_f32_e32 v159, 0xbfb8aa3b, v177
	v_pk_mul_f32 v[186:187], v[34:35], v[202:203] op_sel_hi:[1,0]
	v_pk_mul_f32 v[202:203], v[32:33], v[202:203] op_sel_hi:[1,0]
	v_mul_f32_e32 v160, 0xbfb8aa3b, v160
	v_mul_f32_e32 v161, 0xbfb8aa3b, v161
	v_exp_f32_e32 v99, v99
	v_exp_f32_e32 v159, v159
	v_mul_f32_e32 v176, 0xbfb8aa3b, v202
	v_mul_f32_e32 v177, 0xbfb8aa3b, v203
	v_exp_f32_e32 v160, v160
	v_exp_f32_e32 v161, v161
	v_exp_f32_e32 v176, v176
	v_exp_f32_e32 v177, v177
	v_mul_f32_e32 v186, 0xbfb8aa3b, v186
	v_mul_f32_e32 v187, 0xbfb8aa3b, v187
	v_exp_f32_e32 v186, v186
	v_exp_f32_e32 v187, v187
	v_add_f32_e32 v99, 1.0, v99
	v_add_f32_e32 v159, 1.0, v159
	v_pk_mul_f32 v[100:101], v[100:101], v[100:101]
	v_add_f32_e32 v202, 1.0, v160
	v_add_f32_e32 v203, 1.0, v161
	v_rcp_f32_e32 v160, v99
	v_rcp_f32_e32 v161, v159
	v_pk_mul_f32 v[102:103], v[102:103], v[102:103]
	v_add_f32_e32 v99, v100, v101
	v_add_f32_e32 v204, 1.0, v176
	v_add_f32_e32 v205, 1.0, v177
	v_rcp_f32_e32 v176, v202
	v_rcp_f32_e32 v177, v203
	v_add_f32_e32 v99, v102, v99
	v_pk_mul_f32 v[164:165], v[164:165], v[164:165]
	v_add_f32_e32 v99, v103, v99
	v_add_f32_e32 v206, 1.0, v186
	v_add_f32_e32 v207, 1.0, v187
	v_rcp_f32_e32 v186, v204
	v_rcp_f32_e32 v187, v205
	v_add_f32_e32 v99, v164, v99
	v_add_f32_e32 v99, v165, v99
	v_rcp_f32_e32 v202, v206
	v_rcp_f32_e32 v203, v207
	v_pk_mul_f32 v[204:205], v[166:167], v[166:167]
	s_waitcnt vmcnt(2)
	v_lshlrev_b32_e32 v100, 16, v168
	v_and_b32_e32 v101, 0xffff0000, v168
	v_lshlrev_b32_e32 v102, 16, v169
	v_and_b32_e32 v103, 0xffff0000, v169
	s_waitcnt vmcnt(1)
	v_pk_fma_f32 v[164:165], v[160:161], v[100:101], v[172:173]
	v_pk_fma_f32 v[166:167], v[176:177], v[102:103], v[174:175]
	v_pk_mul_f32 v[100:101], v[164:165], v[164:165]
	v_lshlrev_b32_e32 v168, 16, v170
	v_and_b32_e32 v169, 0xffff0000, v170
	v_pk_mul_f32 v[102:103], v[166:167], v[166:167]
	v_add_f32_e32 v100, v100, v101
	s_waitcnt vmcnt(0)
	v_pk_fma_f32 v[168:169], v[186:187], v[168:169], v[198:199]
	v_add_f32_e32 v100, v102, v100
	v_lshlrev_b32_e32 v170, 16, v171
	v_and_b32_e32 v171, 0xffff0000, v171
	v_pk_mul_f32 v[160:161], v[168:169], v[168:169]
	v_add_f32_e32 v100, v103, v100
	v_pk_fma_f32 v[170:171], v[202:203], v[170:171], v[200:201]
	v_add_f32_e32 v100, v160, v100
	v_pk_mul_f32 v[172:173], v[170:171], v[170:171]
	v_add_f32_e32 v100, v161, v100
	v_add_f32_e32 v99, v204, v99
	v_add_f32_e32 v100, v172, v100
	v_add_f32_e32 v99, v205, v99
	v_add_f32_e32 v100, v173, v100
	v_add_f32_e32 v99, v99, v100
	ds_bpermute_b32 v100, v96, v99
	global_store_dwordx4 v[6:7], v[164:167], off offset:512
	global_store_dwordx4 v[6:7], v[168:171], off offset:528
	s_waitcnt lgkmcnt(0)
	v_add_f32_e32 v99, v99, v100
	ds_bpermute_b32 v100, v98, v99
	s_and_saveexec_b64 s[26:27], s[36:37]
	s_cbranch_execz .LBB0_374
	v_readlane_b32 s16, v247, 48
	v_readlane_b32 s17, v247, 49
	s_waitcnt lgkmcnt(0)
	v_add_f32_e32 v6, v99, v100
	v_lshl_add_u64 v[4:5], v[4:5], 2, s[16:17]
	v_mov_b32_e32 v220, v6
.LBB0_374:
	s_or_b64 exec, exec, s[26:27]
	global_load_dword v99, v[2:3], off offset:576
	v_add_u32_e32 v4, 0x90, v158
	v_ashrrev_i32_e32 v5, 31, v4
	v_lshlrev_b64 v[6:7], 11, v[4:5]
	v_readlane_b32 s16, v249, 23
	v_lshl_add_u64 v[6:7], v[6:7], 0, v[0:1]
	v_readlane_b32 s17, v249, 24
	s_nop 1
	v_lshl_add_u64 v[160:161], v[6:7], 1, s[16:17]
	s_waitcnt lgkmcnt(0)
	global_load_dwordx4 v[100:103], v[160:161], off
	v_lshl_add_u64 v[6:7], v[6:7], 2, s[88:89]
	global_load_dwordx4 v[164:167], v[6:7], off
	global_load_dwordx4 v[168:171], v[6:7], off offset:16
	s_waitcnt vmcnt(3)
	v_fmamk_f32 v99, v99, 0x3a000000, v189
	v_mul_f32_e32 v159, 0x4b800000, v99
	v_cmp_gt_f32_e32 vcc, s2, v99
	s_waitcnt vmcnt(2)
	v_lshlrev_b32_e32 v172, 16, v100
	v_cndmask_b32_e32 v99, v99, v159, vcc
	v_rsq_f32_e32 v99, v99
	v_and_b32_e32 v173, 0xffff0000, v100
	v_lshlrev_b32_e32 v174, 16, v101
	v_and_b32_e32 v175, 0xffff0000, v101
	v_mul_f32_e32 v100, 0x45800000, v99
	v_cndmask_b32_e32 v202, v99, v100, vcc
	v_lshlrev_b32_e32 v176, 16, v102
	v_and_b32_e32 v177, 0xffff0000, v102
	v_lshlrev_b32_e32 v186, 16, v103
	v_and_b32_e32 v187, 0xffff0000, v103
	v_pk_mul_f32 v[100:101], v[94:95], v[202:203] op_sel_hi:[1,0]
	v_pk_mul_f32 v[102:103], v[92:93], v[202:203] op_sel_hi:[1,0]
	v_pk_mul_f32 v[198:199], v[90:91], v[202:203] op_sel_hi:[1,0]
	v_pk_mul_f32 v[200:201], v[88:89], v[202:203] op_sel_hi:[1,0]
	v_mul_f32_e32 v99, 0xbfb8aa3b, v102
	v_mul_f32_e32 v102, 0xbfb8aa3b, v103
	v_mul_f32_e32 v100, 0xbfb8aa3b, v100
	v_mul_f32_e32 v101, 0xbfb8aa3b, v101
	v_mul_f32_e32 v103, 0xbfb8aa3b, v200
	v_mul_f32_e32 v159, 0xbfb8aa3b, v201
	v_mul_f32_e32 v198, 0xbfb8aa3b, v198
	v_mul_f32_e32 v199, 0xbfb8aa3b, v199
	v_exp_f32_e32 v99, v99
	v_exp_f32_e32 v102, v102
	v_exp_f32_e32 v100, v100
	v_exp_f32_e32 v101, v101
	v_exp_f32_e32 v103, v103
	v_exp_f32_e32 v159, v159
	v_exp_f32_e32 v198, v198
	v_exp_f32_e32 v199, v199
	v_add_f32_e32 v99, 1.0, v99
	v_add_f32_e32 v102, 1.0, v102
	v_add_f32_e32 v200, 1.0, v100
	v_add_f32_e32 v201, 1.0, v101
	v_add_f32_e32 v203, 1.0, v103
	v_add_f32_e32 v159, 1.0, v159
	v_add_f32_e32 v204, 1.0, v198
	v_add_f32_e32 v205, 1.0, v199
	v_rcp_f32_e32 v100, v99
	v_rcp_f32_e32 v101, v102
	v_rcp_f32_e32 v102, v200
	v_rcp_f32_e32 v103, v201
	v_rcp_f32_e32 v198, v203
	v_rcp_f32_e32 v199, v159
	v_rcp_f32_e32 v200, v204
	v_rcp_f32_e32 v201, v205
	s_waitcnt vmcnt(1)
	v_pk_fma_f32 v[100:101], v[100:101], v[172:173], v[164:165]
	v_pk_fma_f32 v[102:103], v[102:103], v[174:175], v[166:167]
	s_waitcnt vmcnt(0)
	v_pk_fma_f32 v[164:165], v[198:199], v[176:177], v[168:169]
	v_pk_fma_f32 v[166:167], v[200:201], v[186:187], v[170:171]
	global_store_dwordx4 v[6:7], v[100:103], off
	global_store_dwordx4 v[6:7], v[164:167], off offset:16
	global_load_dwordx4 v[168:171], v[160:161], off offset:256
	global_load_dwordx4 v[172:175], v[6:7], off offset:512
	global_load_dwordx4 v[198:201], v[6:7], off offset:528
	v_pk_mul_f32 v[176:177], v[28:29], v[202:203] op_sel_hi:[1,0]
	v_pk_mul_f32 v[160:161], v[30:31], v[202:203] op_sel_hi:[1,0]
	v_mul_f32_e32 v99, 0xbfb8aa3b, v176
	v_mul_f32_e32 v159, 0xbfb8aa3b, v177
	v_pk_mul_f32 v[186:187], v[26:27], v[202:203] op_sel_hi:[1,0]
	v_pk_mul_f32 v[202:203], v[24:25], v[202:203] op_sel_hi:[1,0]
	v_mul_f32_e32 v160, 0xbfb8aa3b, v160
	v_mul_f32_e32 v161, 0xbfb8aa3b, v161
	v_exp_f32_e32 v99, v99
	v_exp_f32_e32 v159, v159
	v_mul_f32_e32 v176, 0xbfb8aa3b, v202
	v_mul_f32_e32 v177, 0xbfb8aa3b, v203
	v_exp_f32_e32 v160, v160
	v_exp_f32_e32 v161, v161
	v_exp_f32_e32 v176, v176
	v_exp_f32_e32 v177, v177
	v_mul_f32_e32 v186, 0xbfb8aa3b, v186
	v_mul_f32_e32 v187, 0xbfb8aa3b, v187
	v_exp_f32_e32 v186, v186
	v_exp_f32_e32 v187, v187
	v_add_f32_e32 v99, 1.0, v99
	v_add_f32_e32 v159, 1.0, v159
	v_pk_mul_f32 v[100:101], v[100:101], v[100:101]
	v_add_f32_e32 v202, 1.0, v160
	v_add_f32_e32 v203, 1.0, v161
	v_rcp_f32_e32 v160, v99
	v_rcp_f32_e32 v161, v159
	v_pk_mul_f32 v[102:103], v[102:103], v[102:103]
	v_add_f32_e32 v99, v100, v101
	v_add_f32_e32 v204, 1.0, v176
	v_add_f32_e32 v205, 1.0, v177
	v_rcp_f32_e32 v176, v202
	v_rcp_f32_e32 v177, v203
	v_add_f32_e32 v99, v102, v99
	v_pk_mul_f32 v[164:165], v[164:165], v[164:165]
	v_add_f32_e32 v99, v103, v99
	v_add_f32_e32 v206, 1.0, v186
	v_add_f32_e32 v207, 1.0, v187
	v_rcp_f32_e32 v186, v204
	v_rcp_f32_e32 v187, v205
	v_add_f32_e32 v99, v164, v99
	v_add_f32_e32 v99, v165, v99
	v_rcp_f32_e32 v202, v206
	v_rcp_f32_e32 v203, v207
	v_pk_mul_f32 v[204:205], v[166:167], v[166:167]
	s_waitcnt vmcnt(2)
	v_lshlrev_b32_e32 v100, 16, v168
	v_and_b32_e32 v101, 0xffff0000, v168
	v_lshlrev_b32_e32 v102, 16, v169
	v_and_b32_e32 v103, 0xffff0000, v169
	s_waitcnt vmcnt(1)
	v_pk_fma_f32 v[164:165], v[160:161], v[100:101], v[172:173]
	v_pk_fma_f32 v[166:167], v[176:177], v[102:103], v[174:175]
	v_pk_mul_f32 v[100:101], v[164:165], v[164:165]
	v_lshlrev_b32_e32 v168, 16, v170
	v_and_b32_e32 v169, 0xffff0000, v170
	v_pk_mul_f32 v[102:103], v[166:167], v[166:167]
	v_add_f32_e32 v100, v100, v101
	s_waitcnt vmcnt(0)
	v_pk_fma_f32 v[168:169], v[186:187], v[168:169], v[198:199]
	v_add_f32_e32 v100, v102, v100
	v_lshlrev_b32_e32 v170, 16, v171
	v_and_b32_e32 v171, 0xffff0000, v171
	v_pk_mul_f32 v[160:161], v[168:169], v[168:169]
	v_add_f32_e32 v100, v103, v100
	v_pk_fma_f32 v[170:171], v[202:203], v[170:171], v[200:201]
	v_add_f32_e32 v100, v160, v100
	v_pk_mul_f32 v[172:173], v[170:171], v[170:171]
	v_add_f32_e32 v100, v161, v100
	v_add_f32_e32 v99, v204, v99
	v_add_f32_e32 v100, v172, v100
	v_add_f32_e32 v99, v205, v99
	v_add_f32_e32 v100, v173, v100
	v_add_f32_e32 v99, v99, v100
	ds_bpermute_b32 v100, v96, v99
	global_store_dwordx4 v[6:7], v[164:167], off offset:512
	global_store_dwordx4 v[6:7], v[168:171], off offset:528
	s_waitcnt lgkmcnt(0)
	v_add_f32_e32 v99, v99, v100
	ds_bpermute_b32 v100, v98, v99
	s_and_saveexec_b64 s[26:27], s[36:37]
	s_cbranch_execz .LBB0_376
	v_readlane_b32 s16, v247, 48
	v_readlane_b32 s17, v247, 49
	s_waitcnt lgkmcnt(0)
	v_add_f32_e32 v6, v99, v100
	v_lshl_add_u64 v[4:5], v[4:5], 2, s[16:17]
	v_mov_b32_e32 v221, v6
.LBB0_376:
	s_or_b64 exec, exec, s[26:27]
	global_load_dword v99, v[2:3], off offset:640
	v_add_u32_e32 v4, 0xa0, v158
	v_ashrrev_i32_e32 v5, 31, v4
	v_lshlrev_b64 v[6:7], 11, v[4:5]
	v_readlane_b32 s16, v249, 23
	v_lshl_add_u64 v[6:7], v[6:7], 0, v[0:1]
	v_readlane_b32 s17, v249, 24
	s_nop 1
	v_lshl_add_u64 v[160:161], v[6:7], 1, s[16:17]
	s_waitcnt lgkmcnt(0)
	global_load_dwordx4 v[100:103], v[160:161], off
	v_lshl_add_u64 v[6:7], v[6:7], 2, s[88:89]
	global_load_dwordx4 v[164:167], v[6:7], off
	global_load_dwordx4 v[168:171], v[6:7], off offset:16
	s_waitcnt vmcnt(3)
	v_fmamk_f32 v99, v99, 0x3a000000, v189
	v_mul_f32_e32 v159, 0x4b800000, v99
	v_cmp_gt_f32_e32 vcc, s2, v99
	s_waitcnt vmcnt(2)
	v_lshlrev_b32_e32 v172, 16, v100
	v_cndmask_b32_e32 v99, v99, v159, vcc
	v_rsq_f32_e32 v99, v99
	v_and_b32_e32 v173, 0xffff0000, v100
	v_lshlrev_b32_e32 v174, 16, v101
	v_and_b32_e32 v175, 0xffff0000, v101
	v_mul_f32_e32 v100, 0x45800000, v99
	v_cndmask_b32_e32 v202, v99, v100, vcc
	v_lshlrev_b32_e32 v176, 16, v102
	v_and_b32_e32 v177, 0xffff0000, v102
	v_lshlrev_b32_e32 v186, 16, v103
	v_and_b32_e32 v187, 0xffff0000, v103
	v_pk_mul_f32 v[100:101], v[86:87], v[202:203] op_sel_hi:[1,0]
	v_pk_mul_f32 v[102:103], v[84:85], v[202:203] op_sel_hi:[1,0]
	v_pk_mul_f32 v[198:199], v[82:83], v[202:203] op_sel_hi:[1,0]
	v_pk_mul_f32 v[200:201], v[80:81], v[202:203] op_sel_hi:[1,0]
	v_mul_f32_e32 v99, 0xbfb8aa3b, v102
	v_mul_f32_e32 v102, 0xbfb8aa3b, v103
	v_mul_f32_e32 v100, 0xbfb8aa3b, v100
	v_mul_f32_e32 v101, 0xbfb8aa3b, v101
	v_mul_f32_e32 v103, 0xbfb8aa3b, v200
	v_mul_f32_e32 v159, 0xbfb8aa3b, v201
	v_mul_f32_e32 v198, 0xbfb8aa3b, v198
	v_mul_f32_e32 v199, 0xbfb8aa3b, v199
	v_exp_f32_e32 v99, v99
	v_exp_f32_e32 v102, v102
	v_exp_f32_e32 v100, v100
	v_exp_f32_e32 v101, v101
	v_exp_f32_e32 v103, v103
	v_exp_f32_e32 v159, v159
	v_exp_f32_e32 v198, v198
	v_exp_f32_e32 v199, v199
	v_add_f32_e32 v99, 1.0, v99
	v_add_f32_e32 v102, 1.0, v102
	v_add_f32_e32 v200, 1.0, v100
	v_add_f32_e32 v201, 1.0, v101
	v_add_f32_e32 v203, 1.0, v103
	v_add_f32_e32 v159, 1.0, v159
	v_add_f32_e32 v204, 1.0, v198
	v_add_f32_e32 v205, 1.0, v199
	v_rcp_f32_e32 v100, v99
	v_rcp_f32_e32 v101, v102
	v_rcp_f32_e32 v102, v200
	v_rcp_f32_e32 v103, v201
	v_rcp_f32_e32 v198, v203
	v_rcp_f32_e32 v199, v159
	v_rcp_f32_e32 v200, v204
	v_rcp_f32_e32 v201, v205
	s_waitcnt vmcnt(1)
	v_pk_fma_f32 v[100:101], v[100:101], v[172:173], v[164:165]
	v_pk_fma_f32 v[102:103], v[102:103], v[174:175], v[166:167]
	s_waitcnt vmcnt(0)
	v_pk_fma_f32 v[164:165], v[198:199], v[176:177], v[168:169]
	v_pk_fma_f32 v[166:167], v[200:201], v[186:187], v[170:171]
	global_store_dwordx4 v[6:7], v[100:103], off
	global_store_dwordx4 v[6:7], v[164:167], off offset:16
	global_load_dwordx4 v[168:171], v[160:161], off offset:256
	global_load_dwordx4 v[172:175], v[6:7], off offset:512
	global_load_dwordx4 v[198:201], v[6:7], off offset:528
	v_pk_mul_f32 v[176:177], v[20:21], v[202:203] op_sel_hi:[1,0]
	v_pk_mul_f32 v[160:161], v[22:23], v[202:203] op_sel_hi:[1,0]
	v_mul_f32_e32 v99, 0xbfb8aa3b, v176
	v_mul_f32_e32 v159, 0xbfb8aa3b, v177
	v_pk_mul_f32 v[186:187], v[18:19], v[202:203] op_sel_hi:[1,0]
	v_pk_mul_f32 v[202:203], v[16:17], v[202:203] op_sel_hi:[1,0]
	v_mul_f32_e32 v160, 0xbfb8aa3b, v160
	v_mul_f32_e32 v161, 0xbfb8aa3b, v161
	v_exp_f32_e32 v99, v99
	v_exp_f32_e32 v159, v159
	v_mul_f32_e32 v176, 0xbfb8aa3b, v202
	v_mul_f32_e32 v177, 0xbfb8aa3b, v203
	v_exp_f32_e32 v160, v160
	v_exp_f32_e32 v161, v161
	v_exp_f32_e32 v176, v176
	v_exp_f32_e32 v177, v177
	v_mul_f32_e32 v186, 0xbfb8aa3b, v186
	v_mul_f32_e32 v187, 0xbfb8aa3b, v187
	v_exp_f32_e32 v186, v186
	v_exp_f32_e32 v187, v187
	v_add_f32_e32 v99, 1.0, v99
	v_add_f32_e32 v159, 1.0, v159
	v_pk_mul_f32 v[100:101], v[100:101], v[100:101]
	v_add_f32_e32 v202, 1.0, v160
	v_add_f32_e32 v203, 1.0, v161
	v_rcp_f32_e32 v160, v99
	v_rcp_f32_e32 v161, v159
	v_pk_mul_f32 v[102:103], v[102:103], v[102:103]
	v_add_f32_e32 v99, v100, v101
	v_add_f32_e32 v204, 1.0, v176
	v_add_f32_e32 v205, 1.0, v177
	v_rcp_f32_e32 v176, v202
	v_rcp_f32_e32 v177, v203
	v_add_f32_e32 v99, v102, v99
	v_pk_mul_f32 v[164:165], v[164:165], v[164:165]
	v_add_f32_e32 v99, v103, v99
	v_add_f32_e32 v206, 1.0, v186
	v_add_f32_e32 v207, 1.0, v187
	v_rcp_f32_e32 v186, v204
	v_rcp_f32_e32 v187, v205
	v_add_f32_e32 v99, v164, v99
	v_add_f32_e32 v99, v165, v99
	v_rcp_f32_e32 v202, v206
	v_rcp_f32_e32 v203, v207
	v_pk_mul_f32 v[204:205], v[166:167], v[166:167]
	s_waitcnt vmcnt(2)
	v_lshlrev_b32_e32 v100, 16, v168
	v_and_b32_e32 v101, 0xffff0000, v168
	v_lshlrev_b32_e32 v102, 16, v169
	v_and_b32_e32 v103, 0xffff0000, v169
	s_waitcnt vmcnt(1)
	v_pk_fma_f32 v[164:165], v[160:161], v[100:101], v[172:173]
	v_pk_fma_f32 v[166:167], v[176:177], v[102:103], v[174:175]
	v_pk_mul_f32 v[100:101], v[164:165], v[164:165]
	v_lshlrev_b32_e32 v168, 16, v170
	v_and_b32_e32 v169, 0xffff0000, v170
	v_pk_mul_f32 v[102:103], v[166:167], v[166:167]
	v_add_f32_e32 v100, v100, v101
	s_waitcnt vmcnt(0)
	v_pk_fma_f32 v[168:169], v[186:187], v[168:169], v[198:199]
	v_add_f32_e32 v100, v102, v100
	v_lshlrev_b32_e32 v170, 16, v171
	v_and_b32_e32 v171, 0xffff0000, v171
	v_pk_mul_f32 v[160:161], v[168:169], v[168:169]
	v_add_f32_e32 v100, v103, v100
	v_pk_fma_f32 v[170:171], v[202:203], v[170:171], v[200:201]
	v_add_f32_e32 v100, v160, v100
	v_pk_mul_f32 v[172:173], v[170:171], v[170:171]
	v_add_f32_e32 v100, v161, v100
	v_add_f32_e32 v99, v204, v99
	v_add_f32_e32 v100, v172, v100
	v_add_f32_e32 v99, v205, v99
	v_add_f32_e32 v100, v173, v100
	v_add_f32_e32 v99, v99, v100
	ds_bpermute_b32 v100, v96, v99
	global_store_dwordx4 v[6:7], v[164:167], off offset:512
	global_store_dwordx4 v[6:7], v[168:171], off offset:528
	s_waitcnt lgkmcnt(0)
	v_add_f32_e32 v99, v99, v100
	ds_bpermute_b32 v100, v98, v99
	s_and_saveexec_b64 s[26:27], s[36:37]
	s_cbranch_execz .LBB0_378
	v_readlane_b32 s16, v247, 48
	v_readlane_b32 s17, v247, 49
	s_waitcnt lgkmcnt(0)
	v_add_f32_e32 v6, v99, v100
	v_lshl_add_u64 v[4:5], v[4:5], 2, s[16:17]
	v_mov_b32_e32 v222, v6
.LBB0_378:
	s_or_b64 exec, exec, s[26:27]
	global_load_dword v6, v[2:3], off offset:704
	v_add_u32_e32 v4, 0xb0, v158
	v_ashrrev_i32_e32 v5, 31, v4
	v_lshlrev_b64 v[2:3], 11, v[4:5]
	v_readlane_b32 s16, v249, 23
	v_lshl_add_u64 v[0:1], v[2:3], 0, v[0:1]
	v_readlane_b32 s17, v249, 24
	s_waitcnt vmcnt(0)
	v_fmamk_f32 v6, v6, 0x3a000000, v189
	v_lshl_add_u64 v[2:3], v[0:1], 1, s[16:17]
	s_waitcnt lgkmcnt(0)
	global_load_dwordx4 v[100:103], v[2:3], off
	v_lshl_add_u64 v[0:1], v[0:1], 2, s[88:89]
	global_load_dwordx4 v[164:167], v[0:1], off
	global_load_dwordx4 v[168:171], v[0:1], off offset:16
	v_mul_f32_e32 v7, 0x4b800000, v6
	v_cmp_gt_f32_e32 vcc, s2, v6
	s_waitcnt vmcnt(2)
	v_lshlrev_b32_e32 v160, 16, v101
	v_cndmask_b32_e32 v6, v6, v7, vcc
	v_rsq_f32_e32 v99, v6
	v_lshlrev_b32_e32 v6, 16, v100
	v_and_b32_e32 v7, 0xffff0000, v100
	v_and_b32_e32 v161, 0xffff0000, v101
	v_mul_f32_e32 v100, 0x45800000, v99
	v_cndmask_b32_e32 v176, v99, v100, vcc
	v_lshlrev_b32_e32 v172, 16, v102
	v_and_b32_e32 v173, 0xffff0000, v102
	v_lshlrev_b32_e32 v174, 16, v103
	v_and_b32_e32 v175, 0xffff0000, v103
	v_pk_mul_f32 v[100:101], v[78:79], v[176:177] op_sel_hi:[1,0]
	v_pk_mul_f32 v[102:103], v[76:77], v[176:177] op_sel_hi:[1,0]
	v_pk_mul_f32 v[186:187], v[74:75], v[176:177] op_sel_hi:[1,0]
	v_pk_mul_f32 v[198:199], v[72:73], v[176:177] op_sel_hi:[1,0]
	v_mul_f32_e32 v99, 0xbfb8aa3b, v102
	v_mul_f32_e32 v102, 0xbfb8aa3b, v103
	v_mul_f32_e32 v100, 0xbfb8aa3b, v100
	v_mul_f32_e32 v101, 0xbfb8aa3b, v101
	v_mul_f32_e32 v103, 0xbfb8aa3b, v198
	v_mul_f32_e32 v159, 0xbfb8aa3b, v199
	v_mul_f32_e32 v177, 0xbfb8aa3b, v186
	v_mul_f32_e32 v186, 0xbfb8aa3b, v187
	v_exp_f32_e32 v99, v99
	v_exp_f32_e32 v102, v102
	v_exp_f32_e32 v100, v100
	v_exp_f32_e32 v101, v101
	v_exp_f32_e32 v103, v103
	v_exp_f32_e32 v159, v159
	v_exp_f32_e32 v177, v177
	v_exp_f32_e32 v186, v186
	v_add_f32_e32 v99, 1.0, v99
	v_add_f32_e32 v102, 1.0, v102
	v_add_f32_e32 v187, 1.0, v100
	v_add_f32_e32 v198, 1.0, v101
	v_add_f32_e32 v199, 1.0, v103
	v_add_f32_e32 v159, 1.0, v159
	v_add_f32_e32 v177, 1.0, v177
	v_add_f32_e32 v200, 1.0, v186
	v_rcp_f32_e32 v100, v99
	v_rcp_f32_e32 v101, v102
	v_rcp_f32_e32 v102, v187
	v_rcp_f32_e32 v103, v198
	v_rcp_f32_e32 v186, v199
	v_rcp_f32_e32 v187, v159
	v_rcp_f32_e32 v198, v177
	v_rcp_f32_e32 v199, v200
	s_waitcnt vmcnt(1)
	v_pk_fma_f32 v[100:101], v[100:101], v[6:7], v[164:165]
	v_pk_fma_f32 v[102:103], v[102:103], v[160:161], v[166:167]
	s_waitcnt vmcnt(0)
	v_pk_fma_f32 v[164:165], v[186:187], v[172:173], v[168:169]
	v_pk_fma_f32 v[166:167], v[198:199], v[174:175], v[170:171]
	global_store_dwordx4 v[0:1], v[100:103], off
	global_store_dwordx4 v[0:1], v[164:167], off offset:16
	global_load_dwordx4 v[168:171], v[2:3], off offset:256
	global_load_dwordx4 v[172:175], v[0:1], off offset:512
	global_load_dwordx4 v[198:201], v[0:1], off offset:528
	v_pk_mul_f32 v[6:7], v[12:13], v[176:177] op_sel_hi:[1,0]
	v_pk_mul_f32 v[2:3], v[14:15], v[176:177] op_sel_hi:[1,0]
	v_mul_f32_e32 v6, 0xbfb8aa3b, v6
	v_mul_f32_e32 v7, 0xbfb8aa3b, v7
	v_pk_mul_f32 v[160:161], v[10:11], v[176:177] op_sel_hi:[1,0]
	v_pk_mul_f32 v[176:177], v[8:9], v[176:177] op_sel_hi:[1,0]
	v_mul_f32_e32 v2, 0xbfb8aa3b, v2
	v_mul_f32_e32 v3, 0xbfb8aa3b, v3
	v_exp_f32_e32 v6, v6
	v_exp_f32_e32 v7, v7
	v_mul_f32_e32 v99, 0xbfb8aa3b, v176
	v_exp_f32_e32 v2, v2
	v_exp_f32_e32 v3, v3
	v_mul_f32_e32 v159, 0xbfb8aa3b, v177
	v_mul_f32_e32 v160, 0xbfb8aa3b, v160
	v_exp_f32_e32 v99, v99
	v_mul_f32_e32 v161, 0xbfb8aa3b, v161
	v_exp_f32_e32 v159, v159
	v_exp_f32_e32 v160, v160
	v_exp_f32_e32 v161, v161
	v_add_f32_e32 v6, 1.0, v6
	v_add_f32_e32 v7, 1.0, v7
	v_add_f32_e32 v176, 1.0, v2
	v_add_f32_e32 v177, 1.0, v3
	v_rcp_f32_e32 v2, v6
	v_rcp_f32_e32 v3, v7
	v_add_f32_e32 v99, 1.0, v99
	v_rcp_f32_e32 v6, v176
	v_rcp_f32_e32 v7, v177
	v_pk_mul_f32 v[100:101], v[100:101], v[100:101]
	v_add_f32_e32 v159, 1.0, v159
	v_add_f32_e32 v186, 1.0, v160
	v_rcp_f32_e32 v160, v99
	v_pk_mul_f32 v[102:103], v[102:103], v[102:103]
	v_add_f32_e32 v99, v100, v101
	v_add_f32_e32 v187, 1.0, v161
	v_rcp_f32_e32 v161, v159
	v_add_f32_e32 v99, v102, v99
	v_pk_mul_f32 v[164:165], v[164:165], v[164:165]
	v_add_f32_e32 v99, v103, v99
	v_rcp_f32_e32 v176, v186
	v_rcp_f32_e32 v177, v187
	v_add_f32_e32 v99, v164, v99
	v_add_f32_e32 v99, v165, v99
	v_pk_mul_f32 v[186:187], v[166:167], v[166:167]
	s_waitcnt vmcnt(2)
	v_lshlrev_b32_e32 v100, 16, v168
	v_and_b32_e32 v101, 0xffff0000, v168
	v_lshlrev_b32_e32 v102, 16, v169
	v_and_b32_e32 v103, 0xffff0000, v169
	s_waitcnt vmcnt(1)
	v_pk_fma_f32 v[100:101], v[2:3], v[100:101], v[172:173]
	v_pk_fma_f32 v[102:103], v[6:7], v[102:103], v[174:175]
	v_pk_mul_f32 v[2:3], v[100:101], v[100:101]
	v_lshlrev_b32_e32 v164, 16, v170
	v_and_b32_e32 v165, 0xffff0000, v170
	v_pk_mul_f32 v[6:7], v[102:103], v[102:103]
	v_add_f32_e32 v2, v2, v3
	s_waitcnt vmcnt(0)
	v_pk_fma_f32 v[164:165], v[160:161], v[164:165], v[198:199]
	v_add_f32_e32 v2, v6, v2
	v_lshlrev_b32_e32 v166, 16, v171
	v_and_b32_e32 v167, 0xffff0000, v171
	v_pk_mul_f32 v[160:161], v[164:165], v[164:165]
	v_add_f32_e32 v2, v7, v2
	v_pk_fma_f32 v[166:167], v[176:177], v[166:167], v[200:201]
	v_add_f32_e32 v2, v160, v2
	v_pk_mul_f32 v[168:169], v[166:167], v[166:167]
	v_add_f32_e32 v2, v161, v2
	v_add_f32_e32 v99, v186, v99
	v_add_f32_e32 v2, v168, v2
	v_add_f32_e32 v99, v187, v99
	v_add_f32_e32 v2, v169, v2
	v_add_f32_e32 v2, v99, v2
	ds_bpermute_b32 v3, v96, v2
	global_store_dwordx4 v[0:1], v[100:103], off offset:512
	global_store_dwordx4 v[0:1], v[164:167], off offset:528
	s_waitcnt lgkmcnt(0)
	v_add_f32_e32 v2, v2, v3
	ds_bpermute_b32 v3, v98, v2
	s_and_saveexec_b64 s[26:27], s[36:37]
	s_cbranch_execz .LBB0_380
	v_readlane_b32 s16, v247, 48
	v_readlane_b32 s17, v247, 49
	s_waitcnt lgkmcnt(0)
	v_add_f32_e32 v2, v2, v3
	v_lshl_add_u64 v[0:1], v[4:5], 2, s[16:17]
	v_mov_b32_e32 v223, v2
	v_lshlrev_b32_e32 v214, 2, v158
	s_nop 3
	global_atomic_add_f32 v214, v216, s[16:17]
	global_atomic_add_f32 v214, v217, s[16:17] offset:64
	global_atomic_add_f32 v214, v218, s[16:17] offset:128
	global_atomic_add_f32 v214, v219, s[16:17] offset:192
	global_atomic_add_f32 v214, v220, s[16:17] offset:512
	global_atomic_add_f32 v214, v221, s[16:17] offset:576
	global_atomic_add_f32 v214, v222, s[16:17] offset:640
	global_atomic_add_f32 v214, v223, s[16:17] offset:704

.LBB0_428:
	v_and_b32_e32 v5, 64, v196
	v_xor_b32_e32 v4, 16, v196
	v_add_u32_e32 v5, 64, v5
	v_cmp_lt_i32_e32 vcc, v4, v5
	v_ashrrev_i32_e32 v1, 31, v0
	s_waitcnt lgkmcnt(0)
	v_lshl_add_u64 v[2:3], v[0:1], 2, s[44:45]
	v_cndmask_b32_e32 v4, v196, v4, vcc
	v_lshlrev_b32_e32 v98, 2, v4
	v_xor_b32_e32 v4, 32, v196
	v_cmp_lt_i32_e32 vcc, v4, v5
	s_nop 1
	v_cndmask_b32_e32 v4, v196, v4, vcc
	v_lshlrev_b32_e32 v96, 2, v4
	v_lshlrev_b64 v[4:5], 11, v[158:159]
	v_lshl_add_u64 v[4:5], v[4:5], 0, v[0:1]
	v_lshlrev_b64 v[6:7], 2, v[4:5]
	v_lshl_add_u64 v[160:161], s[42:43], 0, v[6:7]
	global_load_dwordx4 v[100:103], v[160:161], off offset:16
	global_load_dwordx4 v[164:167], v[160:161], off
	global_load_dwordx4 v[168:171], v[2:3], off offset:16
	global_load_dwordx4 v[172:175], v[2:3], off
	v_lshl_add_u64 v[6:7], s[88:89], 0, v[6:7]
	v_lshl_add_u64 v[4:5], v[4:5], 1, s[46:47]
	s_waitcnt vmcnt(0)
	v_pk_add_f32 v[100:101], v[136:137], v[100:101]
	v_pk_add_f32 v[164:165], v[140:141], v[164:165]
	v_pk_add_f32 v[166:167], v[142:143], v[166:167]
	v_mul_f32_e32 v99, v165, v165
	v_fmac_f32_e32 v99, v164, v164
	v_fmac_f32_e32 v99, v166, v166
	v_fmac_f32_e32 v99, v167, v167
	v_fmac_f32_e32 v99, v100, v100
	v_pk_add_f32 v[102:103], v[138:139], v[102:103]
	v_fmac_f32_e32 v99, v101, v101
	v_fmac_f32_e32 v99, v102, v102
	global_store_dwordx4 v[6:7], v[164:167], off
	global_store_dwordx4 v[6:7], v[100:103], off offset:16
	v_fmac_f32_e32 v99, v103, v103
	v_pk_mul_f32 v[166:167], v[174:175], v[166:167]
	v_pk_mul_f32 v[164:165], v[172:173], v[164:165]
	v_pk_mul_f32 v[102:103], v[170:171], v[102:103]
	v_pk_mul_f32 v[100:101], v[168:169], v[100:101]
	v_cvt_pk_bf16_f32 v164, v164, v165
	v_cvt_pk_bf16_f32 v165, v166, v167
	v_cvt_pk_bf16_f32 v166, v100, v101
	v_cvt_pk_bf16_f32 v167, v102, v103
	global_store_dwordx4 v[4:5], v[164:167], off
	global_load_dwordx4 v[100:103], v[160:161], off offset:528
	s_nop 0
	global_load_dwordx4 v[164:167], v[160:161], off offset:512
	global_load_dwordx4 v[168:171], v[2:3], off offset:528
	global_load_dwordx4 v[172:175], v[2:3], off offset:512
	s_waitcnt vmcnt(3)
	v_pk_add_f32 v[102:103], v[66:67], v[102:103]
	s_waitcnt vmcnt(2)
	v_pk_add_f32 v[166:167], v[70:71], v[166:167]
	v_pk_add_f32 v[164:165], v[68:69], v[164:165]
	v_pk_add_f32 v[100:101], v[64:65], v[100:101]
	global_store_dwordx4 v[6:7], v[164:167], off offset:512
	global_store_dwordx4 v[6:7], v[100:103], off offset:528
	v_mul_f32_e32 v6, v165, v165
	v_fmac_f32_e32 v6, v164, v164
	v_fmac_f32_e32 v6, v166, v166
	v_fmac_f32_e32 v6, v167, v167
	v_fmac_f32_e32 v6, v100, v100
	v_fmac_f32_e32 v6, v101, v101
	v_fmac_f32_e32 v6, v102, v102
	v_fmac_f32_e32 v6, v103, v103
	v_add_f32_e32 v99, v99, v6
	s_waitcnt vmcnt(2)
	v_pk_mul_f32 v[6:7], v[174:175], v[166:167]
	v_pk_mul_f32 v[160:161], v[172:173], v[164:165]
	v_cvt_pk_bf16_f32 v165, v6, v7
	v_pk_mul_f32 v[6:7], v[170:171], v[102:103]
	v_pk_mul_f32 v[100:101], v[168:169], v[100:101]
	v_cvt_pk_bf16_f32 v164, v160, v161
	v_cvt_pk_bf16_f32 v166, v100, v101
	v_cvt_pk_bf16_f32 v167, v6, v7
	global_store_dwordx4 v[4:5], v[164:167], off offset:256
	ds_bpermute_b32 v4, v98, v99
	s_waitcnt lgkmcnt(0)
	v_add_f32_e32 v4, v99, v4
	ds_bpermute_b32 v5, v96, v4
	s_and_saveexec_b64 s[26:27], s[36:37]
	s_cbranch_execz .LBB0_430
	v_lshl_add_u64 v[6:7], v[158:159], 2, s[10:11]
	s_waitcnt lgkmcnt(0)
	v_add_f32_e32 v4, v4, v5
	v_mov_b32_e32 v216, v4
.LBB0_430:
	s_or_b64 exec, exec, s[26:27]
	v_or_b32_e32 v4, 16, v158
	s_waitcnt lgkmcnt(0)
	v_ashrrev_i32_e32 v5, 31, v4
	v_lshlrev_b64 v[4:5], 11, v[4:5]
	v_lshl_add_u64 v[4:5], v[4:5], 0, v[0:1]
	v_lshlrev_b64 v[6:7], 2, v[4:5]
	v_lshl_add_u64 v[160:161], s[42:43], 0, v[6:7]
	v_lshl_add_u64 v[172:173], s[88:89], 0, v[6:7]
	v_lshl_add_u64 v[174:175], v[4:5], 1, s[46:47]
	global_load_dwordx4 v[4:7], v[160:161], off offset:16
	global_load_dwordx4 v[100:103], v[160:161], off
	global_load_dwordx4 v[164:167], v[2:3], off offset:16
	global_load_dwordx4 v[168:171], v[2:3], off
	s_waitcnt vmcnt(3)
	v_pk_add_f32 v[4:5], v[128:129], v[4:5]
	s_waitcnt vmcnt(2)
	v_pk_add_f32 v[100:101], v[132:133], v[100:101]
	v_pk_add_f32 v[102:103], v[134:135], v[102:103]
	v_mul_f32_e32 v99, v101, v101
	v_fmac_f32_e32 v99, v100, v100
	v_fmac_f32_e32 v99, v102, v102
	v_fmac_f32_e32 v99, v103, v103
	v_fmac_f32_e32 v99, v4, v4
	v_pk_add_f32 v[6:7], v[130:131], v[6:7]
	v_fmac_f32_e32 v99, v5, v5
	v_fmac_f32_e32 v99, v6, v6
	global_store_dwordx4 v[172:173], v[100:103], off
	global_store_dwordx4 v[172:173], v[4:7], off offset:16
	v_fmac_f32_e32 v99, v7, v7
	s_waitcnt vmcnt(2)
	v_pk_mul_f32 v[102:103], v[170:171], v[102:103]
	v_pk_mul_f32 v[100:101], v[168:169], v[100:101]
	v_pk_mul_f32 v[6:7], v[166:167], v[6:7]
	v_pk_mul_f32 v[4:5], v[164:165], v[4:5]
	v_cvt_pk_bf16_f32 v100, v100, v101
	v_cvt_pk_bf16_f32 v101, v102, v103
	v_cvt_pk_bf16_f32 v102, v4, v5
	v_cvt_pk_bf16_f32 v103, v6, v7
	global_store_dwordx4 v[174:175], v[100:103], off
	global_load_dwordx4 v[4:7], v[160:161], off offset:528
	s_nop 0
	global_load_dwordx4 v[100:103], v[160:161], off offset:512
	global_load_dwordx4 v[164:167], v[2:3], off offset:528
	global_load_dwordx4 v[168:171], v[2:3], off offset:512
	s_waitcnt vmcnt(3)
	v_pk_add_f32 v[4:5], v[56:57], v[4:5]
	s_waitcnt vmcnt(2)
	v_pk_add_f32 v[100:101], v[60:61], v[100:101]
	v_pk_add_f32 v[102:103], v[62:63], v[102:103]
	v_mul_f32_e32 v160, v101, v101
	v_fmac_f32_e32 v160, v100, v100
	v_fmac_f32_e32 v160, v102, v102
	v_fmac_f32_e32 v160, v103, v103
	v_fmac_f32_e32 v160, v4, v4
	v_pk_add_f32 v[6:7], v[58:59], v[6:7]
	v_fmac_f32_e32 v160, v5, v5
	v_fmac_f32_e32 v160, v6, v6
	v_fmac_f32_e32 v160, v7, v7
	global_store_dwordx4 v[172:173], v[100:103], off offset:512
	global_store_dwordx4 v[172:173], v[4:7], off offset:528
	v_add_f32_e32 v99, v99, v160
	s_waitcnt vmcnt(2)
	v_pk_mul_f32 v[102:103], v[170:171], v[102:103]
	v_pk_mul_f32 v[100:101], v[168:169], v[100:101]
	v_pk_mul_f32 v[4:5], v[164:165], v[4:5]
	v_cvt_pk_bf16_f32 v100, v100, v101
	v_cvt_pk_bf16_f32 v101, v102, v103
	v_cvt_pk_bf16_f32 v102, v4, v5
	ds_bpermute_b32 v4, v98, v99
	v_pk_mul_f32 v[6:7], v[166:167], v[6:7]
	s_waitcnt lgkmcnt(0)
	v_add_f32_e32 v4, v99, v4
	ds_bpermute_b32 v5, v96, v4
	v_cvt_pk_bf16_f32 v103, v6, v7
	global_store_dwordx4 v[174:175], v[100:103], off offset:256
	s_and_saveexec_b64 s[26:27], s[36:37]
	s_cbranch_execz .LBB0_432
	v_lshl_add_u64 v[6:7], v[158:159], 2, s[10:11]
	s_waitcnt lgkmcnt(0)
	v_add_f32_e32 v4, v4, v5
	v_mov_b32_e32 v217, v4
.LBB0_432:
	s_or_b64 exec, exec, s[26:27]
	v_or_b32_e32 v4, 32, v158
	s_waitcnt lgkmcnt(0)
	v_ashrrev_i32_e32 v5, 31, v4
	v_lshlrev_b64 v[4:5], 11, v[4:5]
	v_lshl_add_u64 v[4:5], v[4:5], 0, v[0:1]
	v_lshlrev_b64 v[6:7], 2, v[4:5]
	v_lshl_add_u64 v[160:161], s[42:43], 0, v[6:7]
	v_lshl_add_u64 v[172:173], s[88:89], 0, v[6:7]
	v_lshl_add_u64 v[174:175], v[4:5], 1, s[46:47]
	global_load_dwordx4 v[4:7], v[160:161], off offset:16
	global_load_dwordx4 v[100:103], v[160:161], off
	global_load_dwordx4 v[164:167], v[2:3], off offset:16
	global_load_dwordx4 v[168:171], v[2:3], off
	s_waitcnt vmcnt(3)
	v_pk_add_f32 v[4:5], v[120:121], v[4:5]
	s_waitcnt vmcnt(2)
	v_pk_add_f32 v[100:101], v[124:125], v[100:101]
	v_pk_add_f32 v[102:103], v[126:127], v[102:103]
	v_mul_f32_e32 v99, v101, v101
	v_fmac_f32_e32 v99, v100, v100
	v_fmac_f32_e32 v99, v102, v102
	v_fmac_f32_e32 v99, v103, v103
	v_fmac_f32_e32 v99, v4, v4
	v_pk_add_f32 v[6:7], v[122:123], v[6:7]
	v_fmac_f32_e32 v99, v5, v5
	v_fmac_f32_e32 v99, v6, v6
	global_store_dwordx4 v[172:173], v[100:103], off
	global_store_dwordx4 v[172:173], v[4:7], off offset:16
	v_fmac_f32_e32 v99, v7, v7
	s_waitcnt vmcnt(2)
	v_pk_mul_f32 v[102:103], v[170:171], v[102:103]
	v_pk_mul_f32 v[100:101], v[168:169], v[100:101]
	v_pk_mul_f32 v[6:7], v[166:167], v[6:7]
	v_pk_mul_f32 v[4:5], v[164:165], v[4:5]
	v_cvt_pk_bf16_f32 v100, v100, v101
	v_cvt_pk_bf16_f32 v101, v102, v103
	v_cvt_pk_bf16_f32 v102, v4, v5
	v_cvt_pk_bf16_f32 v103, v6, v7
	global_store_dwordx4 v[174:175], v[100:103], off
	global_load_dwordx4 v[4:7], v[160:161], off offset:528
	s_nop 0
	global_load_dwordx4 v[100:103], v[160:161], off offset:512
	global_load_dwordx4 v[164:167], v[2:3], off offset:528
	global_load_dwordx4 v[168:171], v[2:3], off offset:512
	s_waitcnt vmcnt(3)
	v_pk_add_f32 v[4:5], v[48:49], v[4:5]
	s_waitcnt vmcnt(2)
	v_pk_add_f32 v[100:101], v[52:53], v[100:101]
	v_pk_add_f32 v[102:103], v[54:55], v[102:103]
	v_mul_f32_e32 v160, v101, v101
	v_fmac_f32_e32 v160, v100, v100
	v_fmac_f32_e32 v160, v102, v102
	v_fmac_f32_e32 v160, v103, v103
	v_fmac_f32_e32 v160, v4, v4
	v_pk_add_f32 v[6:7], v[50:51], v[6:7]
	v_fmac_f32_e32 v160, v5, v5
	v_fmac_f32_e32 v160, v6, v6
	v_fmac_f32_e32 v160, v7, v7
	global_store_dwordx4 v[172:173], v[100:103], off offset:512
	global_store_dwordx4 v[172:173], v[4:7], off offset:528
	v_add_f32_e32 v99, v99, v160
	s_waitcnt vmcnt(2)
	v_pk_mul_f32 v[102:103], v[170:171], v[102:103]
	v_pk_mul_f32 v[100:101], v[168:169], v[100:101]
	v_pk_mul_f32 v[4:5], v[164:165], v[4:5]
	v_cvt_pk_bf16_f32 v100, v100, v101
	v_cvt_pk_bf16_f32 v101, v102, v103
	v_cvt_pk_bf16_f32 v102, v4, v5
	ds_bpermute_b32 v4, v98, v99
	v_pk_mul_f32 v[6:7], v[166:167], v[6:7]
	s_waitcnt lgkmcnt(0)
	v_add_f32_e32 v4, v99, v4
	ds_bpermute_b32 v5, v96, v4
	v_cvt_pk_bf16_f32 v103, v6, v7
	global_store_dwordx4 v[174:175], v[100:103], off offset:256
	s_and_saveexec_b64 s[26:27], s[36:37]
	s_cbranch_execz .LBB0_434
	v_lshl_add_u64 v[6:7], v[158:159], 2, s[10:11]
	s_waitcnt lgkmcnt(0)
	v_add_f32_e32 v4, v4, v5
	v_mov_b32_e32 v218, v4
.LBB0_434:
	s_or_b64 exec, exec, s[26:27]
	v_or_b32_e32 v4, 48, v158
	s_waitcnt lgkmcnt(0)
	v_ashrrev_i32_e32 v5, 31, v4
	v_lshlrev_b64 v[4:5], 11, v[4:5]
	v_lshl_add_u64 v[4:5], v[4:5], 0, v[0:1]
	v_lshlrev_b64 v[6:7], 2, v[4:5]
	v_lshl_add_u64 v[160:161], s[42:43], 0, v[6:7]
	v_lshl_add_u64 v[172:173], s[88:89], 0, v[6:7]
	v_lshl_add_u64 v[174:175], v[4:5], 1, s[46:47]
	global_load_dwordx4 v[4:7], v[160:161], off offset:16
	global_load_dwordx4 v[100:103], v[160:161], off
	global_load_dwordx4 v[164:167], v[2:3], off offset:16
	global_load_dwordx4 v[168:171], v[2:3], off
	s_waitcnt vmcnt(3)
	v_pk_add_f32 v[4:5], v[112:113], v[4:5]
	s_waitcnt vmcnt(2)
	v_pk_add_f32 v[100:101], v[116:117], v[100:101]
	v_pk_add_f32 v[102:103], v[118:119], v[102:103]
	v_mul_f32_e32 v99, v101, v101
	v_fmac_f32_e32 v99, v100, v100
	v_fmac_f32_e32 v99, v102, v102
	v_fmac_f32_e32 v99, v103, v103
	v_fmac_f32_e32 v99, v4, v4
	v_pk_add_f32 v[6:7], v[114:115], v[6:7]
	v_fmac_f32_e32 v99, v5, v5
	v_fmac_f32_e32 v99, v6, v6
	global_store_dwordx4 v[172:173], v[100:103], off
	global_store_dwordx4 v[172:173], v[4:7], off offset:16
	v_fmac_f32_e32 v99, v7, v7
	s_waitcnt vmcnt(2)
	v_pk_mul_f32 v[102:103], v[170:171], v[102:103]
	v_pk_mul_f32 v[100:101], v[168:169], v[100:101]
	v_pk_mul_f32 v[6:7], v[166:167], v[6:7]
	v_pk_mul_f32 v[4:5], v[164:165], v[4:5]
	v_cvt_pk_bf16_f32 v100, v100, v101
	v_cvt_pk_bf16_f32 v101, v102, v103
	v_cvt_pk_bf16_f32 v102, v4, v5
	v_cvt_pk_bf16_f32 v103, v6, v7
	global_store_dwordx4 v[174:175], v[100:103], off
	global_load_dwordx4 v[4:7], v[160:161], off offset:528
	s_nop 0
	global_load_dwordx4 v[100:103], v[160:161], off offset:512
	global_load_dwordx4 v[164:167], v[2:3], off offset:528
	global_load_dwordx4 v[168:171], v[2:3], off offset:512
	s_waitcnt vmcnt(3)
	v_pk_add_f32 v[4:5], v[40:41], v[4:5]
	s_waitcnt vmcnt(2)
	v_pk_add_f32 v[100:101], v[44:45], v[100:101]
	v_pk_add_f32 v[102:103], v[46:47], v[102:103]
	v_mul_f32_e32 v160, v101, v101
	v_fmac_f32_e32 v160, v100, v100
	v_fmac_f32_e32 v160, v102, v102
	v_fmac_f32_e32 v160, v103, v103
	v_fmac_f32_e32 v160, v4, v4
	v_pk_add_f32 v[6:7], v[42:43], v[6:7]
	v_fmac_f32_e32 v160, v5, v5
	v_fmac_f32_e32 v160, v6, v6
	v_fmac_f32_e32 v160, v7, v7
	global_store_dwordx4 v[172:173], v[100:103], off offset:512
	global_store_dwordx4 v[172:173], v[4:7], off offset:528
	v_add_f32_e32 v99, v99, v160
	s_waitcnt vmcnt(2)
	v_pk_mul_f32 v[102:103], v[170:171], v[102:103]
	v_pk_mul_f32 v[100:101], v[168:169], v[100:101]
	v_pk_mul_f32 v[4:5], v[164:165], v[4:5]
	v_cvt_pk_bf16_f32 v100, v100, v101
	v_cvt_pk_bf16_f32 v101, v102, v103
	v_cvt_pk_bf16_f32 v102, v4, v5
	ds_bpermute_b32 v4, v98, v99
	v_pk_mul_f32 v[6:7], v[166:167], v[6:7]
	s_waitcnt lgkmcnt(0)
	v_add_f32_e32 v4, v99, v4
	ds_bpermute_b32 v5, v96, v4
	v_cvt_pk_bf16_f32 v103, v6, v7
	global_store_dwordx4 v[174:175], v[100:103], off offset:256
	s_and_saveexec_b64 s[26:27], s[36:37]
	s_cbranch_execz .LBB0_436
	v_lshl_add_u64 v[6:7], v[158:159], 2, s[10:11]
	s_waitcnt lgkmcnt(0)
	v_add_f32_e32 v4, v4, v5
	v_mov_b32_e32 v219, v4
.LBB0_436:
	s_or_b64 exec, exec, s[26:27]
	s_waitcnt lgkmcnt(0)
	v_lshlrev_b64 v[4:5], 11, v[158:159]
	v_lshl_add_u64 v[4:5], v[4:5], 0, v[0:1]
	s_mov_b64 s[26:27], 0x40000
	v_lshl_add_u64 v[6:7], v[4:5], 0, s[26:27]
	v_lshlrev_b64 v[100:101], 2, v[6:7]
	v_lshl_add_u64 v[160:161], s[42:43], 0, v[100:101]
	v_lshl_add_u64 v[176:177], s[88:89], 0, v[100:101]
	global_load_dwordx4 v[100:103], v[160:161], off offset:16
	global_load_dwordx4 v[164:167], v[160:161], off
	global_load_dwordx4 v[168:171], v[2:3], off offset:16
	global_load_dwordx4 v[172:175], v[2:3], off
	v_lshl_add_u64 v[6:7], v[6:7], 1, s[46:47]
	s_waitcnt vmcnt(3)
	v_pk_add_f32 v[100:101], v[104:105], v[100:101]
	s_waitcnt vmcnt(2)
	v_pk_add_f32 v[164:165], v[108:109], v[164:165]
	v_pk_add_f32 v[166:167], v[110:111], v[166:167]
	v_mul_f32_e32 v99, v165, v165
	v_fmac_f32_e32 v99, v164, v164
	v_fmac_f32_e32 v99, v166, v166
	v_fmac_f32_e32 v99, v167, v167
	v_fmac_f32_e32 v99, v100, v100
	v_pk_add_f32 v[102:103], v[106:107], v[102:103]
	v_fmac_f32_e32 v99, v101, v101
	v_fmac_f32_e32 v99, v102, v102
	global_store_dwordx4 v[176:177], v[164:167], off
	global_store_dwordx4 v[176:177], v[100:103], off offset:16
	v_fmac_f32_e32 v99, v103, v103
	s_waitcnt vmcnt(2)
	v_pk_mul_f32 v[166:167], v[174:175], v[166:167]
	v_pk_mul_f32 v[164:165], v[172:173], v[164:165]
	v_pk_mul_f32 v[102:103], v[170:171], v[102:103]
	v_pk_mul_f32 v[100:101], v[168:169], v[100:101]
	v_cvt_pk_bf16_f32 v164, v164, v165
	v_cvt_pk_bf16_f32 v165, v166, v167
	v_cvt_pk_bf16_f32 v166, v100, v101
	v_cvt_pk_bf16_f32 v167, v102, v103
	global_store_dwordx4 v[6:7], v[164:167], off
	global_load_dwordx4 v[100:103], v[160:161], off offset:528
	s_nop 0
	global_load_dwordx4 v[164:167], v[160:161], off offset:512
	global_load_dwordx4 v[168:171], v[2:3], off offset:528
	global_load_dwordx4 v[172:175], v[2:3], off offset:512
	s_waitcnt vmcnt(3)
	v_pk_add_f32 v[100:101], v[32:33], v[100:101]
	s_waitcnt vmcnt(2)
	v_pk_add_f32 v[164:165], v[36:37], v[164:165]
	v_pk_add_f32 v[166:167], v[38:39], v[166:167]
	v_mul_f32_e32 v160, v165, v165
	v_fmac_f32_e32 v160, v164, v164
	v_fmac_f32_e32 v160, v166, v166
	v_fmac_f32_e32 v160, v167, v167
	v_fmac_f32_e32 v160, v100, v100
	v_pk_add_f32 v[102:103], v[34:35], v[102:103]
	v_fmac_f32_e32 v160, v101, v101
	v_fmac_f32_e32 v160, v102, v102
	v_fmac_f32_e32 v160, v103, v103
	global_store_dwordx4 v[176:177], v[164:167], off offset:512
	global_store_dwordx4 v[176:177], v[100:103], off offset:528
	v_add_f32_e32 v99, v99, v160
	s_waitcnt vmcnt(2)
	v_pk_mul_f32 v[160:161], v[174:175], v[166:167]
	v_pk_mul_f32 v[164:165], v[172:173], v[164:165]
	v_pk_mul_f32 v[102:103], v[170:171], v[102:103]
	v_pk_mul_f32 v[100:101], v[168:169], v[100:101]
	v_cvt_pk_bf16_f32 v164, v164, v165
	v_cvt_pk_bf16_f32 v165, v160, v161
	v_cvt_pk_bf16_f32 v166, v100, v101
	v_cvt_pk_bf16_f32 v167, v102, v103
	global_store_dwordx4 v[6:7], v[164:167], off offset:256
	ds_bpermute_b32 v6, v98, v99
	s_waitcnt lgkmcnt(0)
	v_add_f32_e32 v6, v99, v6
	ds_bpermute_b32 v7, v96, v6
	s_and_saveexec_b64 s[26:27], s[36:37]
	s_cbranch_execz .LBB0_438
	v_lshl_add_u64 v[100:101], v[158:159], 2, s[10:11]
	s_waitcnt lgkmcnt(0)
	v_add_f32_e32 v6, v6, v7
	v_mov_b32_e32 v220, v6
.LBB0_438:
	s_or_b64 exec, exec, s[26:27]
	s_mov_b64 s[26:27], 0x48000
	v_lshl_add_u64 v[4:5], v[4:5], 0, s[26:27]
	s_waitcnt lgkmcnt(0)
	v_lshlrev_b64 v[6:7], 2, v[4:5]
	v_lshl_add_u64 v[160:161], s[42:43], 0, v[6:7]
	v_lshl_add_u64 v[172:173], s[88:89], 0, v[6:7]
	v_lshl_add_u64 v[174:175], v[4:5], 1, s[46:47]
	global_load_dwordx4 v[4:7], v[160:161], off offset:16
	global_load_dwordx4 v[100:103], v[160:161], off
	global_load_dwordx4 v[164:167], v[2:3], off offset:16
	global_load_dwordx4 v[168:171], v[2:3], off
	s_waitcnt vmcnt(3)
	v_pk_add_f32 v[4:5], v[88:89], v[4:5]
	s_waitcnt vmcnt(2)
	v_pk_add_f32 v[100:101], v[92:93], v[100:101]
	v_pk_add_f32 v[102:103], v[94:95], v[102:103]
	v_mul_f32_e32 v99, v101, v101
	v_fmac_f32_e32 v99, v100, v100
	v_fmac_f32_e32 v99, v102, v102
	v_fmac_f32_e32 v99, v103, v103
	v_fmac_f32_e32 v99, v4, v4
	v_pk_add_f32 v[6:7], v[90:91], v[6:7]
	v_fmac_f32_e32 v99, v5, v5
	v_fmac_f32_e32 v99, v6, v6
	global_store_dwordx4 v[172:173], v[100:103], off
	global_store_dwordx4 v[172:173], v[4:7], off offset:16
	v_fmac_f32_e32 v99, v7, v7
	s_waitcnt vmcnt(2)
	v_pk_mul_f32 v[102:103], v[170:171], v[102:103]
	v_pk_mul_f32 v[100:101], v[168:169], v[100:101]
	v_pk_mul_f32 v[6:7], v[166:167], v[6:7]
	v_pk_mul_f32 v[4:5], v[164:165], v[4:5]
	v_cvt_pk_bf16_f32 v100, v100, v101
	v_cvt_pk_bf16_f32 v101, v102, v103
	v_cvt_pk_bf16_f32 v102, v4, v5
	v_cvt_pk_bf16_f32 v103, v6, v7
	global_store_dwordx4 v[174:175], v[100:103], off
	global_load_dwordx4 v[4:7], v[160:161], off offset:528
	s_nop 0
	global_load_dwordx4 v[100:103], v[160:161], off offset:512
	global_load_dwordx4 v[164:167], v[2:3], off offset:528
	global_load_dwordx4 v[168:171], v[2:3], off offset:512
	s_waitcnt vmcnt(3)
	v_pk_add_f32 v[4:5], v[24:25], v[4:5]
	s_waitcnt vmcnt(2)
	v_pk_add_f32 v[100:101], v[28:29], v[100:101]
	v_pk_add_f32 v[102:103], v[30:31], v[102:103]
	v_mul_f32_e32 v160, v101, v101
	v_fmac_f32_e32 v160, v100, v100
	v_fmac_f32_e32 v160, v102, v102
	v_fmac_f32_e32 v160, v103, v103
	v_fmac_f32_e32 v160, v4, v4
	v_pk_add_f32 v[6:7], v[26:27], v[6:7]
	v_fmac_f32_e32 v160, v5, v5
	v_fmac_f32_e32 v160, v6, v6
	v_fmac_f32_e32 v160, v7, v7
	global_store_dwordx4 v[172:173], v[100:103], off offset:512
	global_store_dwordx4 v[172:173], v[4:7], off offset:528
	v_add_f32_e32 v99, v99, v160
	s_waitcnt vmcnt(2)
	v_pk_mul_f32 v[102:103], v[170:171], v[102:103]
	v_pk_mul_f32 v[100:101], v[168:169], v[100:101]
	v_pk_mul_f32 v[4:5], v[164:165], v[4:5]
	v_cvt_pk_bf16_f32 v100, v100, v101
	v_cvt_pk_bf16_f32 v101, v102, v103
	v_cvt_pk_bf16_f32 v102, v4, v5
	ds_bpermute_b32 v4, v98, v99
	v_pk_mul_f32 v[6:7], v[166:167], v[6:7]
	s_waitcnt lgkmcnt(0)
	v_add_f32_e32 v4, v99, v4
	ds_bpermute_b32 v5, v96, v4
	v_cvt_pk_bf16_f32 v103, v6, v7
	global_store_dwordx4 v[174:175], v[100:103], off offset:256
	s_and_saveexec_b64 s[26:27], s[36:37]
	s_cbranch_execz .LBB0_440
	v_lshl_add_u64 v[6:7], v[158:159], 2, s[10:11]
	s_waitcnt lgkmcnt(0)
	v_add_f32_e32 v4, v4, v5
	v_mov_b32_e32 v221, v4
.LBB0_440:
	s_or_b64 exec, exec, s[26:27]
	s_waitcnt lgkmcnt(0)
	v_lshlrev_b64 v[4:5], 11, v[158:159]
	v_lshl_add_u64 v[4:5], v[4:5], 0, v[0:1]
	s_mov_b64 s[26:27], 0x50000
	v_lshl_add_u64 v[6:7], v[4:5], 0, s[26:27]
	v_lshlrev_b64 v[100:101], 2, v[6:7]
	v_lshl_add_u64 v[160:161], s[42:43], 0, v[100:101]
	v_lshl_add_u64 v[176:177], s[88:89], 0, v[100:101]
	global_load_dwordx4 v[100:103], v[160:161], off offset:16
	global_load_dwordx4 v[164:167], v[160:161], off
	global_load_dwordx4 v[168:171], v[2:3], off offset:16
	global_load_dwordx4 v[172:175], v[2:3], off
	v_lshl_add_u64 v[6:7], v[6:7], 1, s[46:47]
	s_waitcnt vmcnt(3)
	v_pk_add_f32 v[100:101], v[80:81], v[100:101]
	s_waitcnt vmcnt(2)
	v_pk_add_f32 v[164:165], v[84:85], v[164:165]
	v_pk_add_f32 v[166:167], v[86:87], v[166:167]
	v_mul_f32_e32 v1, v165, v165
	v_fmac_f32_e32 v1, v164, v164
	v_fmac_f32_e32 v1, v166, v166
	v_fmac_f32_e32 v1, v167, v167
	v_fmac_f32_e32 v1, v100, v100
	v_pk_add_f32 v[102:103], v[82:83], v[102:103]
	v_fmac_f32_e32 v1, v101, v101
	v_fmac_f32_e32 v1, v102, v102
	global_store_dwordx4 v[176:177], v[164:167], off
	global_store_dwordx4 v[176:177], v[100:103], off offset:16
	v_fmac_f32_e32 v1, v103, v103
	s_waitcnt vmcnt(2)
	v_pk_mul_f32 v[166:167], v[174:175], v[166:167]
	v_pk_mul_f32 v[164:165], v[172:173], v[164:165]
	v_pk_mul_f32 v[102:103], v[170:171], v[102:103]
	v_pk_mul_f32 v[100:101], v[168:169], v[100:101]
	v_cvt_pk_bf16_f32 v164, v164, v165
	v_cvt_pk_bf16_f32 v165, v166, v167
	v_cvt_pk_bf16_f32 v166, v100, v101
	v_cvt_pk_bf16_f32 v167, v102, v103
	global_store_dwordx4 v[6:7], v[164:167], off
	global_load_dwordx4 v[100:103], v[160:161], off offset:528
	s_nop 0
	global_load_dwordx4 v[164:167], v[160:161], off offset:512
	global_load_dwordx4 v[168:171], v[2:3], off offset:528
	global_load_dwordx4 v[172:175], v[2:3], off offset:512
	s_waitcnt vmcnt(3)
	v_pk_add_f32 v[100:101], v[16:17], v[100:101]
	s_waitcnt vmcnt(2)
	v_pk_add_f32 v[164:165], v[20:21], v[164:165]
	v_pk_add_f32 v[166:167], v[22:23], v[166:167]
	v_mul_f32_e32 v99, v165, v165
	v_fmac_f32_e32 v99, v164, v164
	v_fmac_f32_e32 v99, v166, v166
	v_fmac_f32_e32 v99, v167, v167
	v_fmac_f32_e32 v99, v100, v100
	v_pk_add_f32 v[102:103], v[18:19], v[102:103]
	v_fmac_f32_e32 v99, v101, v101
	v_fmac_f32_e32 v99, v102, v102
	global_store_dwordx4 v[176:177], v[164:167], off offset:512
	global_store_dwordx4 v[176:177], v[100:103], off offset:528
	v_fmac_f32_e32 v99, v103, v103
	s_waitcnt vmcnt(2)
	v_pk_mul_f32 v[160:161], v[174:175], v[166:167]
	v_pk_mul_f32 v[164:165], v[172:173], v[164:165]
	v_pk_mul_f32 v[102:103], v[170:171], v[102:103]
	v_pk_mul_f32 v[100:101], v[168:169], v[100:101]
	v_add_f32_e32 v1, v1, v99
	v_cvt_pk_bf16_f32 v164, v164, v165
	v_cvt_pk_bf16_f32 v165, v160, v161
	v_cvt_pk_bf16_f32 v166, v100, v101
	v_cvt_pk_bf16_f32 v167, v102, v103
	global_store_dwordx4 v[6:7], v[164:167], off offset:256
	ds_bpermute_b32 v6, v98, v1
	s_waitcnt lgkmcnt(0)
	v_add_f32_e32 v1, v1, v6
	ds_bpermute_b32 v6, v96, v1
	s_and_saveexec_b64 s[26:27], s[36:37]
	s_cbranch_execz .LBB0_442
	v_lshl_add_u64 v[100:101], v[158:159], 2, s[10:11]
	s_waitcnt lgkmcnt(0)
	v_add_f32_e32 v1, v1, v6
	v_mov_b32_e32 v222, v1
.LBB0_442:
	s_or_b64 exec, exec, s[26:27]
	s_mov_b64 s[26:27], 0x58000
	v_lshl_add_u64 v[4:5], v[4:5], 0, s[26:27]
	s_waitcnt lgkmcnt(0)
	v_lshlrev_b64 v[6:7], 2, v[4:5]
	v_lshl_add_u64 v[160:161], s[42:43], 0, v[6:7]
	v_lshl_add_u64 v[172:173], s[88:89], 0, v[6:7]
	v_lshl_add_u64 v[174:175], v[4:5], 1, s[46:47]
	global_load_dwordx4 v[4:7], v[160:161], off offset:16
	global_load_dwordx4 v[100:103], v[160:161], off
	global_load_dwordx4 v[164:167], v[2:3], off offset:16
	global_load_dwordx4 v[168:171], v[2:3], off
	s_waitcnt vmcnt(3)
	v_pk_add_f32 v[4:5], v[72:73], v[4:5]
	s_waitcnt vmcnt(2)
	v_pk_add_f32 v[100:101], v[76:77], v[100:101]
	v_pk_add_f32 v[102:103], v[78:79], v[102:103]
	v_mul_f32_e32 v1, v101, v101
	v_fmac_f32_e32 v1, v100, v100
	v_fmac_f32_e32 v1, v102, v102
	v_fmac_f32_e32 v1, v103, v103
	v_fmac_f32_e32 v1, v4, v4
	v_pk_add_f32 v[6:7], v[74:75], v[6:7]
	v_fmac_f32_e32 v1, v5, v5
	v_fmac_f32_e32 v1, v6, v6
	global_store_dwordx4 v[172:173], v[100:103], off
	global_store_dwordx4 v[172:173], v[4:7], off offset:16
	v_fmac_f32_e32 v1, v7, v7
	s_waitcnt vmcnt(2)
	v_pk_mul_f32 v[102:103], v[170:171], v[102:103]
	v_pk_mul_f32 v[100:101], v[168:169], v[100:101]
	v_pk_mul_f32 v[6:7], v[166:167], v[6:7]
	v_pk_mul_f32 v[4:5], v[164:165], v[4:5]
	v_cvt_pk_bf16_f32 v100, v100, v101
	v_cvt_pk_bf16_f32 v101, v102, v103
	v_cvt_pk_bf16_f32 v102, v4, v5
	v_cvt_pk_bf16_f32 v103, v6, v7
	global_store_dwordx4 v[174:175], v[100:103], off
	global_load_dwordx4 v[4:7], v[160:161], off offset:528
	s_nop 0
	global_load_dwordx4 v[100:103], v[160:161], off offset:512
	global_load_dwordx4 v[164:167], v[2:3], off offset:528
	global_load_dwordx4 v[168:171], v[2:3], off offset:512
	s_waitcnt vmcnt(3)
	v_pk_add_f32 v[4:5], v[8:9], v[4:5]
	s_waitcnt vmcnt(2)
	v_pk_add_f32 v[100:101], v[12:13], v[100:101]
	v_pk_add_f32 v[102:103], v[14:15], v[102:103]
	v_mul_f32_e32 v2, v101, v101
	v_fmac_f32_e32 v2, v100, v100
	v_fmac_f32_e32 v2, v102, v102
	v_fmac_f32_e32 v2, v103, v103
	v_fmac_f32_e32 v2, v4, v4
	v_pk_add_f32 v[6:7], v[10:11], v[6:7]
	v_fmac_f32_e32 v2, v5, v5
	v_fmac_f32_e32 v2, v6, v6
	v_fmac_f32_e32 v2, v7, v7
	global_store_dwordx4 v[172:173], v[100:103], off offset:512
	global_store_dwordx4 v[172:173], v[4:7], off offset:528
	v_add_f32_e32 v1, v1, v2
	s_waitcnt vmcnt(2)
	v_pk_mul_f32 v[102:103], v[170:171], v[102:103]
	v_pk_mul_f32 v[2:3], v[168:169], v[100:101]
	v_pk_mul_f32 v[6:7], v[166:167], v[6:7]
	v_pk_mul_f32 v[4:5], v[164:165], v[4:5]
	v_cvt_pk_bf16_f32 v2, v2, v3
	v_cvt_pk_bf16_f32 v3, v102, v103
	v_cvt_pk_bf16_f32 v4, v4, v5
	v_cvt_pk_bf16_f32 v5, v6, v7
	global_store_dwordx4 v[174:175], v[2:5], off offset:256
	ds_bpermute_b32 v2, v98, v1
	s_waitcnt lgkmcnt(0)
	v_add_f32_e32 v1, v1, v2
	ds_bpermute_b32 v2, v96, v1
	s_and_saveexec_b64 s[26:27], s[36:37]
	s_cbranch_execz .LBB0_444
	v_lshl_add_u64 v[4:5], v[158:159], 2, s[10:11]
	s_waitcnt lgkmcnt(0)
	v_add_f32_e32 v1, v1, v2
	v_mov_b32_e32 v223, v1
	v_lshlrev_b32_e32 v214, 2, v158
	global_atomic_add_f32 v214, v216, s[10:11]
	global_atomic_add_f32 v214, v217, s[10:11] offset:64
	global_atomic_add_f32 v214, v218, s[10:11] offset:128
	global_atomic_add_f32 v214, v219, s[10:11] offset:192
	global_atomic_add_f32 v214, v220, s[10:11] offset:512
	global_atomic_add_f32 v214, v221, s[10:11] offset:576
	global_atomic_add_f32 v214, v222, s[10:11] offset:640
	global_atomic_add_f32 v214, v223, s[10:11] offset:704
